# transpose items mapped k-major inside a workgroup (1 KiB contiguous per output row); P0 conversion by the hand-written routine
# baseline (speedup 1.0000x reference)
.LBB0_73:
	s_mov_b32 s99, 0xc800
	s_cmp_eq_u32 s87, 0x100
	s_cselect_b32 s99, 0x4000, s99
	s_add_i32 s98, s99, -1
	s_lshl_b32 s0, s96, 3
	s_add_i32 s20, s93, s0
	s_cmp_gt_i32 s20, s98
	s_waitcnt lgkmcnt(0)
	s_barrier
	s_cbranch_scc1 .LBB0_158
	s_cmp_lg_u32 s87, 0x100
	s_cbranch_scc1 .Lp0_orig
	s_cmp_lg_u32 s87, 0x100
	s_cbranch_scc1 .Ltp0_done
	s_cmp_lt_u32 s96, 0
	s_cbranch_scc1 .Ltp0_done
	s_cmp_ge_u32 s96, 256
	s_cbranch_scc1 .Ltp0_done
	s_sub_u32 s20, s96, 0
	s_lshl_b32 s20, s20, 3
	s_add_u32 s20, s20, s93
	s_movk_i32 s23, 2048
	v_mbcnt_hi_u32_b32 v0, -1, v212
	v_and_b32_e32 v0, 63, v0
	v_lshrrev_b32_e32 v1, 3, v0
	v_and_b32_e32 v2, 7, v0
	s_lshl_b32 s25, s93, 14
	v_mul_u32_u24_e32 v3, 0x84, v1
	v_mul_u32_u24_e32 v4, 0x420, v2
	v_lshlrev_b32_e32 v2, 4, v2
	v_add3_u32 v3, v3, v2, s25
	v_lshl_add_u32 v4, v1, 2, v4
	v_add_u32_e32 v4, s25, v4
	v_and_b32_e32 v7, 4, v1
	v_and_b32_e32 v5, 3, v1
	v_lshl_add_u32 v7, v7, 1, v5
	v_readlane_b32 s62, v244, 23
	v_readlane_b32 s63, v244, 24
	s_add_u32 s64, s76, 0x189000
	s_addc_u32 s65, s77, 0
	v_readlane_b32 s66, v244, 25
	v_readlane_b32 s67, v244, 26
	s_add_u32 s68, s76, 0x2189000
	s_addc_u32 s69, s77, 0
	v_readlane_b32 s70, v244, 37
	v_readlane_b32 s71, v244, 38
	s_add_u32 s82, s76, 0x2989000
	s_addc_u32 s83, s77, 0
	s_cmp_ge_u32 s20, 16384
	s_cbranch_scc1 .Ltp0_done
	s_cmp_lt_u32 s20, 8192
	s_cbranch_scc1 .Ltp0_r1_s0
	s_cmp_lt_u32 s20, 10240
	s_cbranch_scc1 .Ltp0_r1_s1
	s_sub_u32 s25, s20, 10240
	s_and_b32 s41, s25, 7
	s_lshr_b32 s25, s25, 3
	s_mul_i32 s27, s25, 0xaaab
	s_lshr_b32 s27, s27, 23
	s_mul_i32 s31, s27, 192
	s_sub_u32 s31, s25, s31
	s_lshl_b32 s27, s27, 3
	s_add_u32 s27, s27, s41
	s_mul_i32 s35, s27, 0x180000
	s_lshl_b32 s41, s31, 7
	s_add_u32 s35, s35, s41
	s_add_u32 s0, s70, s35
	s_addc_u32 s1, s71, 0
	s_lshl_b32 s35, s31, 5
	s_mov_b32 s45, 0
	s_cmp_ge_u32 s31, 128
	s_cbranch_scc1 .Ltp0_r1_np
	s_and_b32 s41, s35, 32
	s_lshl_b32 s41, s41, 1
	s_and_b32 s45, s35, 64
	s_lshr_b32 s45, s45, 4
	s_add_u32 s41, s41, s45
	s_andn2_b32 s35, s35, 0x7f
	s_add_u32 s35, s35, s41
	s_mov_b32 s45, 1

.Ltp0_r1_s1:
	s_sub_u32 s25, s20, 8192
	s_and_b32 s41, s25, 7
	s_lshr_b32 s25, s25, 3
	s_lshr_b32 s27, s25, 6
	s_and_b32 s31, s25, 63
	s_lshl_b32 s27, s27, 3
	s_add_u32 s27, s27, s41
	s_mul_i32 s35, s27, 0x80000
	s_lshl_b32 s41, s31, 7
	s_add_u32 s35, s35, s41
	s_add_u32 s0, s66, s35
	s_addc_u32 s1, s67, 0
	s_mov_b32 s45, 0
	s_mul_i32 s35, s31, 0x20000
	s_lshl_b32 s41, s27, 7
	s_add_u32 s35, s35, s41
	s_add_u32 s2, s68, s35
	s_addc_u32 s3, s69, 0
	s_mov_b32 s5, 0x2000
	s_mov_b32 s6, 0x10000
	s_mov_b32 s7, 0x1000
	s_branch .Ltp0_r1_e
.Ltp0_r1_s0:
	s_sub_u32 s25, s20, 0
	s_and_b32 s41, s25, 7
	s_lshr_b32 s25, s25, 3
	s_lshr_b32 s27, s25, 8
	s_and_b32 s31, s25, 255
	s_lshl_b32 s27, s27, 3
	s_add_u32 s27, s27, s41
	s_mul_i32 s35, s27, 0x200000
	s_lshl_b32 s41, s31, 7
	s_add_u32 s35, s35, s41
	s_add_u32 s0, s62, s35
	s_addc_u32 s1, s63, 0
	s_mov_b32 s45, 0
	s_mul_i32 s35, s31, 0x20000
	s_lshl_b32 s41, s27, 7
	s_add_u32 s35, s35, s41
	s_add_u32 s2, s64, s35
	s_addc_u32 s3, s65, 0
	s_mov_b32 s5, 0x8000
	s_mov_b32 s6, 0x40000
	s_mov_b32 s7, 0x1000
.Ltp0_r1_e:
	v_mad_u32_u24 v5, v1, s5, v2
	global_load_dwordx4 v[8:11], v5, s[0:1] nt
	s_add_u32 s0, s0, s6
	s_addc_u32 s1, s1, 0
	global_load_dwordx4 v[12:15], v5, s[0:1] nt
	s_add_u32 s0, s0, s6
	s_addc_u32 s1, s1, 0
	global_load_dwordx4 v[16:19], v5, s[0:1] nt
	s_add_u32 s0, s0, s6
	s_addc_u32 s1, s1, 0
	global_load_dwordx4 v[20:23], v5, s[0:1] nt
	s_add_u32 s0, s0, s6
	s_addc_u32 s1, s1, 0
	global_load_dwordx4 v[24:27], v5, s[0:1] nt
	s_add_u32 s0, s0, s6
	s_addc_u32 s1, s1, 0
	global_load_dwordx4 v[28:31], v5, s[0:1] nt
	s_add_u32 s0, s0, s6
	s_addc_u32 s1, s1, 0
	global_load_dwordx4 v[32:35], v5, s[0:1] nt
	s_add_u32 s0, s0, s6
	s_addc_u32 s1, s1, 0
	global_load_dwordx4 v[36:39], v5, s[0:1] nt
	s_add_u32 s0, s0, s6
	s_addc_u32 s1, s1, 0
	s_add_u32 s20, s20, s23
	s_cmp_ge_u32 s20, 16384
	s_cbranch_scc1 .Ltp0_dr1
	s_cmp_lt_u32 s20, 8192
	s_cbranch_scc1 .Ltp0_r2_s0
	s_cmp_lt_u32 s20, 10240
	s_cbranch_scc1 .Ltp0_r2_s1
	s_sub_u32 s25, s20, 10240
	s_and_b32 s41, s25, 7
	s_lshr_b32 s25, s25, 3
	s_mul_i32 s27, s25, 0xaaab
	s_lshr_b32 s27, s27, 23
	s_mul_i32 s31, s27, 192
	s_sub_u32 s31, s25, s31
	s_lshl_b32 s27, s27, 3
	s_add_u32 s27, s27, s41
	s_mul_i32 s35, s27, 0x180000
	s_lshl_b32 s41, s31, 7
	s_add_u32 s35, s35, s41
	s_add_u32 s0, s70, s35
	s_addc_u32 s1, s71, 0
	s_lshl_b32 s35, s31, 5
	s_mov_b32 s50, 0
	s_cmp_ge_u32 s31, 128
	s_cbranch_scc1 .Ltp0_r2_np
	s_and_b32 s41, s35, 32
	s_lshl_b32 s41, s41, 1
	s_and_b32 s50, s35, 64
	s_lshr_b32 s50, s50, 4
	s_add_u32 s41, s41, s50
	s_andn2_b32 s35, s35, 0x7f
	s_add_u32 s35, s35, s41
	s_mov_b32 s50, 1

.Ltp0_r2_s1:
	s_sub_u32 s25, s20, 8192
	s_and_b32 s41, s25, 7
	s_lshr_b32 s25, s25, 3
	s_lshr_b32 s27, s25, 6
	s_and_b32 s31, s25, 63
	s_lshl_b32 s27, s27, 3
	s_add_u32 s27, s27, s41
	s_mul_i32 s35, s27, 0x80000
	s_lshl_b32 s41, s31, 7
	s_add_u32 s35, s35, s41
	s_add_u32 s0, s66, s35
	s_addc_u32 s1, s67, 0
	s_mov_b32 s50, 0
	s_mul_i32 s35, s31, 0x20000
	s_lshl_b32 s41, s27, 7
	s_add_u32 s35, s35, s41
	s_add_u32 s10, s68, s35
	s_addc_u32 s11, s69, 0
	s_mov_b32 s5, 0x2000
	s_mov_b32 s6, 0x10000
	s_mov_b32 s47, 0x1000
	s_branch .Ltp0_r2_e
.Ltp0_r2_s0:
	s_sub_u32 s25, s20, 0
	s_and_b32 s41, s25, 7
	s_lshr_b32 s25, s25, 3
	s_lshr_b32 s27, s25, 8
	s_and_b32 s31, s25, 255
	s_lshl_b32 s27, s27, 3
	s_add_u32 s27, s27, s41
	s_mul_i32 s35, s27, 0x200000
	s_lshl_b32 s41, s31, 7
	s_add_u32 s35, s35, s41
	s_add_u32 s0, s62, s35
	s_addc_u32 s1, s63, 0
	s_mov_b32 s50, 0
	s_mul_i32 s35, s31, 0x20000
	s_lshl_b32 s41, s27, 7
	s_add_u32 s35, s35, s41
	s_add_u32 s10, s64, s35
	s_addc_u32 s11, s65, 0
	s_mov_b32 s5, 0x8000
	s_mov_b32 s6, 0x40000
	s_mov_b32 s47, 0x1000
.Ltp0_r2_e:
	v_mad_u32_u24 v5, v1, s5, v2
	global_load_dwordx4 v[40:43], v5, s[0:1] nt
	s_add_u32 s0, s0, s6
	s_addc_u32 s1, s1, 0
	global_load_dwordx4 v[44:47], v5, s[0:1] nt
	s_add_u32 s0, s0, s6
	s_addc_u32 s1, s1, 0
	global_load_dwordx4 v[48:51], v5, s[0:1] nt
	s_add_u32 s0, s0, s6
	s_addc_u32 s1, s1, 0
	global_load_dwordx4 v[52:55], v5, s[0:1] nt
	s_add_u32 s0, s0, s6
	s_addc_u32 s1, s1, 0
	global_load_dwordx4 v[56:59], v5, s[0:1] nt
	s_add_u32 s0, s0, s6
	s_addc_u32 s1, s1, 0
	global_load_dwordx4 v[60:63], v5, s[0:1] nt
	s_add_u32 s0, s0, s6
	s_addc_u32 s1, s1, 0
	global_load_dwordx4 v[64:67], v5, s[0:1] nt
	s_add_u32 s0, s0, s6
	s_addc_u32 s1, s1, 0
	global_load_dwordx4 v[68:71], v5, s[0:1] nt
	s_add_u32 s0, s0, s6
	s_addc_u32 s1, s1, 0
	s_add_u32 s20, s20, s23
	s_cmp_ge_u32 s20, 16384
	s_cbranch_scc1 .Ltp0_dr2
	s_cmp_lt_u32 s20, 8192
	s_cbranch_scc1 .Ltp0_r3_s0
	s_cmp_lt_u32 s20, 10240
	s_cbranch_scc1 .Ltp0_r3_s1
	s_sub_u32 s25, s20, 10240
	s_and_b32 s41, s25, 7
	s_lshr_b32 s25, s25, 3
	s_mul_i32 s27, s25, 0xaaab
	s_lshr_b32 s27, s27, 23
	s_mul_i32 s31, s27, 192
	s_sub_u32 s31, s25, s31
	s_lshl_b32 s27, s27, 3
	s_add_u32 s27, s27, s41
	s_mul_i32 s35, s27, 0x180000
	s_lshl_b32 s41, s31, 7
	s_add_u32 s35, s35, s41
	s_add_u32 s0, s70, s35
	s_addc_u32 s1, s71, 0
	s_lshl_b32 s35, s31, 5
	s_mov_b32 s52, 0
	s_cmp_ge_u32 s31, 128
	s_cbranch_scc1 .Ltp0_r3_np
	s_and_b32 s41, s35, 32
	s_lshl_b32 s41, s41, 1
	s_and_b32 s52, s35, 64
	s_lshr_b32 s52, s52, 4
	s_add_u32 s41, s41, s52
	s_andn2_b32 s35, s35, 0x7f
	s_add_u32 s35, s35, s41
	s_mov_b32 s52, 1

.Ltp0_r3_s1:
	s_sub_u32 s25, s20, 8192
	s_and_b32 s41, s25, 7
	s_lshr_b32 s25, s25, 3
	s_lshr_b32 s27, s25, 6
	s_and_b32 s31, s25, 63
	s_lshl_b32 s27, s27, 3
	s_add_u32 s27, s27, s41
	s_mul_i32 s35, s27, 0x80000
	s_lshl_b32 s41, s31, 7
	s_add_u32 s35, s35, s41
	s_add_u32 s0, s66, s35
	s_addc_u32 s1, s67, 0
	s_mov_b32 s52, 0
	s_mul_i32 s35, s31, 0x20000
	s_lshl_b32 s41, s27, 7
	s_add_u32 s35, s35, s41
	s_add_u32 s42, s68, s35
	s_addc_u32 s43, s69, 0
	s_mov_b32 s5, 0x2000
	s_mov_b32 s6, 0x10000
	s_mov_b32 s44, 0x1000
	s_branch .Ltp0_r3_e
.Ltp0_r3_s0:
	s_sub_u32 s25, s20, 0
	s_and_b32 s41, s25, 7
	s_lshr_b32 s25, s25, 3
	s_lshr_b32 s27, s25, 8
	s_and_b32 s31, s25, 255
	s_lshl_b32 s27, s27, 3
	s_add_u32 s27, s27, s41
	s_mul_i32 s35, s27, 0x200000
	s_lshl_b32 s41, s31, 7
	s_add_u32 s35, s35, s41
	s_add_u32 s0, s62, s35
	s_addc_u32 s1, s63, 0
	s_mov_b32 s52, 0
	s_mul_i32 s35, s31, 0x20000
	s_lshl_b32 s41, s27, 7
	s_add_u32 s35, s35, s41
	s_add_u32 s42, s64, s35
	s_addc_u32 s43, s65, 0
	s_mov_b32 s5, 0x8000
	s_mov_b32 s6, 0x40000
	s_mov_b32 s44, 0x1000
.Ltp0_r3_e:
	v_mad_u32_u24 v5, v1, s5, v2
	global_load_dwordx4 v[72:75], v5, s[0:1] nt
	s_add_u32 s0, s0, s6
	s_addc_u32 s1, s1, 0
	global_load_dwordx4 v[76:79], v5, s[0:1] nt
	s_add_u32 s0, s0, s6
	s_addc_u32 s1, s1, 0
	global_load_dwordx4 v[80:83], v5, s[0:1] nt
	s_add_u32 s0, s0, s6
	s_addc_u32 s1, s1, 0
	global_load_dwordx4 v[84:87], v5, s[0:1] nt
	s_add_u32 s0, s0, s6
	s_addc_u32 s1, s1, 0
	global_load_dwordx4 v[88:91], v5, s[0:1] nt
	s_add_u32 s0, s0, s6
	s_addc_u32 s1, s1, 0
	global_load_dwordx4 v[92:95], v5, s[0:1] nt
	s_add_u32 s0, s0, s6
	s_addc_u32 s1, s1, 0
	global_load_dwordx4 v[96:99], v5, s[0:1] nt
	s_add_u32 s0, s0, s6
	s_addc_u32 s1, s1, 0
	global_load_dwordx4 v[100:103], v5, s[0:1] nt
	s_add_u32 s0, s0, s6
	s_addc_u32 s1, s1, 0
	s_add_u32 s20, s20, s23
	s_waitcnt vmcnt(16)
	ds_write_b32 v3, v8 offset:0
	ds_write_b32 v3, v9 offset:4
	ds_write_b32 v3, v10 offset:8
	ds_write_b32 v3, v11 offset:12
	ds_write_b32 v3, v12 offset:1056
	ds_write_b32 v3, v13 offset:1060
	ds_write_b32 v3, v14 offset:1064
	ds_write_b32 v3, v15 offset:1068
	ds_write_b32 v3, v16 offset:2112
	ds_write_b32 v3, v17 offset:2116
	ds_write_b32 v3, v18 offset:2120
	ds_write_b32 v3, v19 offset:2124
	ds_write_b32 v3, v20 offset:3168
	ds_write_b32 v3, v21 offset:3172
	ds_write_b32 v3, v22 offset:3176
	ds_write_b32 v3, v23 offset:3180
	ds_write_b32 v3, v24 offset:4224
	ds_write_b32 v3, v25 offset:4228
	ds_write_b32 v3, v26 offset:4232
	ds_write_b32 v3, v27 offset:4236
	ds_write_b32 v3, v28 offset:5280
	ds_write_b32 v3, v29 offset:5284
	ds_write_b32 v3, v30 offset:5288
	ds_write_b32 v3, v31 offset:5292
	ds_write_b32 v3, v32 offset:6336
	ds_write_b32 v3, v33 offset:6340
	ds_write_b32 v3, v34 offset:6344
	ds_write_b32 v3, v35 offset:6348
	ds_write_b32 v3, v36 offset:7392
	ds_write_b32 v3, v37 offset:7396
	ds_write_b32 v3, v38 offset:7400
	ds_write_b32 v3, v39 offset:7404
	s_mov_b32 s32, s2
	s_mov_b32 s33, s3
	s_lshl_b32 s49, s7, 3
	s_lshl_b32 s41, s49, 1
	s_cmp_lg_u32 s45, 0
	s_cselect_b64 vcc, -1, 0
	s_cselect_b32 s49, s41, s49
	v_cndmask_b32_e32 v6, v1, v7, vcc
	v_mad_u32_u24 v6, v6, s7, v2
	s_waitcnt lgkmcnt(0)
	ds_read_b32 v104, v4 offset:0
	ds_read_b32 v105, v4 offset:132
	ds_read_b32 v106, v4 offset:264
	ds_read_b32 v107, v4 offset:396
	ds_read_b32 v108, v4 offset:528
	ds_read_b32 v109, v4 offset:660
	ds_read_b32 v110, v4 offset:792
	ds_read_b32 v111, v4 offset:924
	ds_read_b32 v112, v4 offset:32
	ds_read_b32 v113, v4 offset:164
	ds_read_b32 v114, v4 offset:296
	ds_read_b32 v115, v4 offset:428
	ds_read_b32 v116, v4 offset:560
	ds_read_b32 v117, v4 offset:692
	ds_read_b32 v118, v4 offset:824
	ds_read_b32 v119, v4 offset:956
	s_waitcnt lgkmcnt(8)
	v_cvt_pk_bf16_f32 v136, v104, v105
	v_cvt_pk_bf16_f32 v137, v106, v107
	v_cvt_pk_bf16_f32 v138, v108, v109
	v_cvt_pk_bf16_f32 v139, v110, v111
	global_store_dwordx4 v6, v[136:139], s[32:33] nt
	s_add_u32 s32, s32, s49
	s_addc_u32 s33, s33, 0
	ds_read_b32 v120, v4 offset:64
	ds_read_b32 v121, v4 offset:196
	ds_read_b32 v122, v4 offset:328
	ds_read_b32 v123, v4 offset:460
	ds_read_b32 v124, v4 offset:592
	ds_read_b32 v125, v4 offset:724
	ds_read_b32 v126, v4 offset:856
	ds_read_b32 v127, v4 offset:988
	s_waitcnt lgkmcnt(8)
	v_cvt_pk_bf16_f32 v140, v112, v113
	v_cvt_pk_bf16_f32 v141, v114, v115
	v_cvt_pk_bf16_f32 v142, v116, v117
	v_cvt_pk_bf16_f32 v143, v118, v119
	global_store_dwordx4 v6, v[140:143], s[32:33] nt
	s_add_u32 s32, s32, s49
	s_addc_u32 s33, s33, 0
	ds_read_b32 v128, v4 offset:96
	ds_read_b32 v129, v4 offset:228
	ds_read_b32 v130, v4 offset:360
	ds_read_b32 v131, v4 offset:492
	ds_read_b32 v132, v4 offset:624
	ds_read_b32 v133, v4 offset:756
	ds_read_b32 v134, v4 offset:888
	ds_read_b32 v135, v4 offset:1020
	s_waitcnt lgkmcnt(8)
	v_cvt_pk_bf16_f32 v136, v120, v121
	v_cvt_pk_bf16_f32 v137, v122, v123
	v_cvt_pk_bf16_f32 v138, v124, v125
	v_cvt_pk_bf16_f32 v139, v126, v127
	global_store_dwordx4 v6, v[136:139], s[32:33] nt
	s_add_u32 s32, s32, s49
	s_addc_u32 s33, s33, 0
	s_waitcnt lgkmcnt(0)
	v_cvt_pk_bf16_f32 v140, v128, v129
	v_cvt_pk_bf16_f32 v141, v130, v131
	v_cvt_pk_bf16_f32 v142, v132, v133
	v_cvt_pk_bf16_f32 v143, v134, v135
	global_store_dwordx4 v6, v[140:143], s[32:33] nt
	s_add_u32 s32, s32, s49
	s_addc_u32 s33, s33, 0
	s_cmp_ge_u32 s20, 16384
	s_cbranch_scc1 .Ltp0_dr3
	s_cmp_lt_u32 s20, 8192
	s_cbranch_scc1 .Ltp0_r4_s0
	s_cmp_lt_u32 s20, 10240
	s_cbranch_scc1 .Ltp0_r4_s1
	s_sub_u32 s25, s20, 10240
	s_and_b32 s41, s25, 7
	s_lshr_b32 s25, s25, 3
	s_mul_i32 s27, s25, 0xaaab
	s_lshr_b32 s27, s27, 23
	s_mul_i32 s31, s27, 192
	s_sub_u32 s31, s25, s31
	s_lshl_b32 s27, s27, 3
	s_add_u32 s27, s27, s41
	s_mul_i32 s35, s27, 0x180000
	s_lshl_b32 s41, s31, 7
	s_add_u32 s35, s35, s41
	s_add_u32 s0, s70, s35
	s_addc_u32 s1, s71, 0
	s_lshl_b32 s35, s31, 5
	s_mov_b32 s45, 0
	s_cmp_ge_u32 s31, 128
	s_cbranch_scc1 .Ltp0_r4_np
	s_and_b32 s41, s35, 32
	s_lshl_b32 s41, s41, 1
	s_and_b32 s45, s35, 64
	s_lshr_b32 s45, s45, 4
	s_add_u32 s41, s41, s45
	s_andn2_b32 s35, s35, 0x7f
	s_add_u32 s35, s35, s41
	s_mov_b32 s45, 1

.Ltp0_loop:
	s_cmp_ge_u32 s20, 16384
	s_cbranch_scc1 .Ltp0_dr4
	s_cmp_lt_u32 s20, 8192
	s_cbranch_scc1 .Ltp0_r5_s0
	s_cmp_lt_u32 s20, 10240
	s_cbranch_scc1 .Ltp0_r5_s1
	s_sub_u32 s25, s20, 10240
	s_and_b32 s41, s25, 7
	s_lshr_b32 s25, s25, 3
	s_mul_i32 s27, s25, 0xaaab
	s_lshr_b32 s27, s27, 23
	s_mul_i32 s31, s27, 192
	s_sub_u32 s31, s25, s31
	s_lshl_b32 s27, s27, 3
	s_add_u32 s27, s27, s41
	s_mul_i32 s35, s27, 0x180000
	s_lshl_b32 s41, s31, 7
	s_add_u32 s35, s35, s41
	s_add_u32 s0, s70, s35
	s_addc_u32 s1, s71, 0
	s_lshl_b32 s35, s31, 5
	s_mov_b32 s50, 0
	s_cmp_ge_u32 s31, 128
	s_cbranch_scc1 .Ltp0_r5_np
	s_and_b32 s41, s35, 32
	s_lshl_b32 s41, s41, 1
	s_and_b32 s50, s35, 64
	s_lshr_b32 s50, s50, 4
	s_add_u32 s41, s41, s50
	s_andn2_b32 s35, s35, 0x7f
	s_add_u32 s35, s35, s41
	s_mov_b32 s50, 1

.Ltp0_r5_e:
	v_mad_u32_u24 v5, v1, s5, v2
	global_load_dwordx4 v[40:43], v5, s[0:1] nt
	s_add_u32 s0, s0, s6
	s_addc_u32 s1, s1, 0
	global_load_dwordx4 v[44:47], v5, s[0:1] nt
	s_add_u32 s0, s0, s6
	s_addc_u32 s1, s1, 0
	global_load_dwordx4 v[48:51], v5, s[0:1] nt
	s_add_u32 s0, s0, s6
	s_addc_u32 s1, s1, 0
	global_load_dwordx4 v[52:55], v5, s[0:1] nt
	s_add_u32 s0, s0, s6
	s_addc_u32 s1, s1, 0
	global_load_dwordx4 v[56:59], v5, s[0:1] nt
	s_add_u32 s0, s0, s6
	s_addc_u32 s1, s1, 0
	global_load_dwordx4 v[60:63], v5, s[0:1] nt
	s_add_u32 s0, s0, s6
	s_addc_u32 s1, s1, 0
	global_load_dwordx4 v[64:67], v5, s[0:1] nt
	s_add_u32 s0, s0, s6
	s_addc_u32 s1, s1, 0
	global_load_dwordx4 v[68:71], v5, s[0:1] nt
	s_add_u32 s0, s0, s6
	s_addc_u32 s1, s1, 0
	s_add_u32 s20, s20, s23
	s_waitcnt vmcnt(24)
	ds_write_b32 v3, v72 offset:0
	ds_write_b32 v3, v73 offset:4
	ds_write_b32 v3, v74 offset:8
	ds_write_b32 v3, v75 offset:12
	ds_write_b32 v3, v76 offset:1056
	ds_write_b32 v3, v77 offset:1060
	ds_write_b32 v3, v78 offset:1064
	ds_write_b32 v3, v79 offset:1068
	ds_write_b32 v3, v80 offset:2112
	ds_write_b32 v3, v81 offset:2116
	ds_write_b32 v3, v82 offset:2120
	ds_write_b32 v3, v83 offset:2124
	ds_write_b32 v3, v84 offset:3168
	ds_write_b32 v3, v85 offset:3172
	ds_write_b32 v3, v86 offset:3176
	ds_write_b32 v3, v87 offset:3180
	ds_write_b32 v3, v88 offset:4224
	ds_write_b32 v3, v89 offset:4228
	ds_write_b32 v3, v90 offset:4232
	ds_write_b32 v3, v91 offset:4236
	ds_write_b32 v3, v92 offset:5280
	ds_write_b32 v3, v93 offset:5284
	ds_write_b32 v3, v94 offset:5288
	ds_write_b32 v3, v95 offset:5292
	ds_write_b32 v3, v96 offset:6336
	ds_write_b32 v3, v97 offset:6340
	ds_write_b32 v3, v98 offset:6344
	ds_write_b32 v3, v99 offset:6348
	ds_write_b32 v3, v100 offset:7392
	ds_write_b32 v3, v101 offset:7396
	ds_write_b32 v3, v102 offset:7400
	ds_write_b32 v3, v103 offset:7404
	s_mov_b32 s32, s42
	s_mov_b32 s33, s43
	s_lshl_b32 s49, s44, 3
	s_lshl_b32 s41, s49, 1
	s_cmp_lg_u32 s52, 0
	s_cselect_b64 vcc, -1, 0
	s_cselect_b32 s49, s41, s49
	v_cndmask_b32_e32 v6, v1, v7, vcc
	v_mad_u32_u24 v6, v6, s44, v2
	s_waitcnt lgkmcnt(0)
	ds_read_b32 v104, v4 offset:0
	ds_read_b32 v105, v4 offset:132
	ds_read_b32 v106, v4 offset:264
	ds_read_b32 v107, v4 offset:396
	ds_read_b32 v108, v4 offset:528
	ds_read_b32 v109, v4 offset:660
	ds_read_b32 v110, v4 offset:792
	ds_read_b32 v111, v4 offset:924
	ds_read_b32 v112, v4 offset:32
	ds_read_b32 v113, v4 offset:164
	ds_read_b32 v114, v4 offset:296
	ds_read_b32 v115, v4 offset:428
	ds_read_b32 v116, v4 offset:560
	ds_read_b32 v117, v4 offset:692
	ds_read_b32 v118, v4 offset:824
	ds_read_b32 v119, v4 offset:956
	s_waitcnt lgkmcnt(8)
	v_cvt_pk_bf16_f32 v136, v104, v105
	v_cvt_pk_bf16_f32 v137, v106, v107
	v_cvt_pk_bf16_f32 v138, v108, v109
	v_cvt_pk_bf16_f32 v139, v110, v111
	global_store_dwordx4 v6, v[136:139], s[32:33] nt
	s_add_u32 s32, s32, s49
	s_addc_u32 s33, s33, 0
	ds_read_b32 v120, v4 offset:64
	ds_read_b32 v121, v4 offset:196
	ds_read_b32 v122, v4 offset:328
	ds_read_b32 v123, v4 offset:460
	ds_read_b32 v124, v4 offset:592
	ds_read_b32 v125, v4 offset:724
	ds_read_b32 v126, v4 offset:856
	ds_read_b32 v127, v4 offset:988
	s_waitcnt lgkmcnt(8)
	v_cvt_pk_bf16_f32 v140, v112, v113
	v_cvt_pk_bf16_f32 v141, v114, v115
	v_cvt_pk_bf16_f32 v142, v116, v117
	v_cvt_pk_bf16_f32 v143, v118, v119
	global_store_dwordx4 v6, v[140:143], s[32:33] nt
	s_add_u32 s32, s32, s49
	s_addc_u32 s33, s33, 0
	ds_read_b32 v128, v4 offset:96
	ds_read_b32 v129, v4 offset:228
	ds_read_b32 v130, v4 offset:360
	ds_read_b32 v131, v4 offset:492
	ds_read_b32 v132, v4 offset:624
	ds_read_b32 v133, v4 offset:756
	ds_read_b32 v134, v4 offset:888
	ds_read_b32 v135, v4 offset:1020
	s_waitcnt lgkmcnt(8)
	v_cvt_pk_bf16_f32 v136, v120, v121
	v_cvt_pk_bf16_f32 v137, v122, v123
	v_cvt_pk_bf16_f32 v138, v124, v125
	v_cvt_pk_bf16_f32 v139, v126, v127
	global_store_dwordx4 v6, v[136:139], s[32:33] nt
	s_add_u32 s32, s32, s49
	s_addc_u32 s33, s33, 0
	s_waitcnt lgkmcnt(0)
	v_cvt_pk_bf16_f32 v140, v128, v129
	v_cvt_pk_bf16_f32 v141, v130, v131
	v_cvt_pk_bf16_f32 v142, v132, v133
	v_cvt_pk_bf16_f32 v143, v134, v135
	global_store_dwordx4 v6, v[140:143], s[32:33] nt
	s_add_u32 s32, s32, s49
	s_addc_u32 s33, s33, 0
	s_cmp_ge_u32 s20, 16384
	s_cbranch_scc1 .Ltp0_dr5
	s_cmp_lt_u32 s20, 8192
	s_cbranch_scc1 .Ltp0_r6_s0
	s_cmp_lt_u32 s20, 10240
	s_cbranch_scc1 .Ltp0_r6_s1
	s_sub_u32 s25, s20, 10240
	s_and_b32 s41, s25, 7
	s_lshr_b32 s25, s25, 3
	s_mul_i32 s27, s25, 0xaaab
	s_lshr_b32 s27, s27, 23
	s_mul_i32 s31, s27, 192
	s_sub_u32 s31, s25, s31
	s_lshl_b32 s27, s27, 3
	s_add_u32 s27, s27, s41
	s_mul_i32 s35, s27, 0x180000
	s_lshl_b32 s41, s31, 7
	s_add_u32 s35, s35, s41
	s_add_u32 s0, s70, s35
	s_addc_u32 s1, s71, 0
	s_lshl_b32 s35, s31, 5
	s_mov_b32 s52, 0
	s_cmp_ge_u32 s31, 128
	s_cbranch_scc1 .Ltp0_r6_np
	s_and_b32 s41, s35, 32
	s_lshl_b32 s41, s41, 1
	s_and_b32 s52, s35, 64
	s_lshr_b32 s52, s52, 4
	s_add_u32 s41, s41, s52
	s_andn2_b32 s35, s35, 0x7f
	s_add_u32 s35, s35, s41
	s_mov_b32 s52, 1

.Ltp0_r6_e:
	v_mad_u32_u24 v5, v1, s5, v2
	global_load_dwordx4 v[72:75], v5, s[0:1] nt
	s_add_u32 s0, s0, s6
	s_addc_u32 s1, s1, 0
	global_load_dwordx4 v[76:79], v5, s[0:1] nt
	s_add_u32 s0, s0, s6
	s_addc_u32 s1, s1, 0
	global_load_dwordx4 v[80:83], v5, s[0:1] nt
	s_add_u32 s0, s0, s6
	s_addc_u32 s1, s1, 0
	global_load_dwordx4 v[84:87], v5, s[0:1] nt
	s_add_u32 s0, s0, s6
	s_addc_u32 s1, s1, 0
	global_load_dwordx4 v[88:91], v5, s[0:1] nt
	s_add_u32 s0, s0, s6
	s_addc_u32 s1, s1, 0
	global_load_dwordx4 v[92:95], v5, s[0:1] nt
	s_add_u32 s0, s0, s6
	s_addc_u32 s1, s1, 0
	global_load_dwordx4 v[96:99], v5, s[0:1] nt
	s_add_u32 s0, s0, s6
	s_addc_u32 s1, s1, 0
	global_load_dwordx4 v[100:103], v5, s[0:1] nt
	s_add_u32 s0, s0, s6
	s_addc_u32 s1, s1, 0
	s_add_u32 s20, s20, s23
	s_waitcnt vmcnt(24)
	ds_write_b32 v3, v8 offset:0
	ds_write_b32 v3, v9 offset:4
	ds_write_b32 v3, v10 offset:8
	ds_write_b32 v3, v11 offset:12
	ds_write_b32 v3, v12 offset:1056
	ds_write_b32 v3, v13 offset:1060
	ds_write_b32 v3, v14 offset:1064
	ds_write_b32 v3, v15 offset:1068
	ds_write_b32 v3, v16 offset:2112
	ds_write_b32 v3, v17 offset:2116
	ds_write_b32 v3, v18 offset:2120
	ds_write_b32 v3, v19 offset:2124
	ds_write_b32 v3, v20 offset:3168
	ds_write_b32 v3, v21 offset:3172
	ds_write_b32 v3, v22 offset:3176
	ds_write_b32 v3, v23 offset:3180
	ds_write_b32 v3, v24 offset:4224
	ds_write_b32 v3, v25 offset:4228
	ds_write_b32 v3, v26 offset:4232
	ds_write_b32 v3, v27 offset:4236
	ds_write_b32 v3, v28 offset:5280
	ds_write_b32 v3, v29 offset:5284
	ds_write_b32 v3, v30 offset:5288
	ds_write_b32 v3, v31 offset:5292
	ds_write_b32 v3, v32 offset:6336
	ds_write_b32 v3, v33 offset:6340
	ds_write_b32 v3, v34 offset:6344
	ds_write_b32 v3, v35 offset:6348
	ds_write_b32 v3, v36 offset:7392
	ds_write_b32 v3, v37 offset:7396
	ds_write_b32 v3, v38 offset:7400
	ds_write_b32 v3, v39 offset:7404
	s_mov_b32 s32, s2
	s_mov_b32 s33, s3
	s_lshl_b32 s49, s7, 3
	s_lshl_b32 s41, s49, 1
	s_cmp_lg_u32 s45, 0
	s_cselect_b64 vcc, -1, 0
	s_cselect_b32 s49, s41, s49
	v_cndmask_b32_e32 v6, v1, v7, vcc
	v_mad_u32_u24 v6, v6, s7, v2
	s_waitcnt lgkmcnt(0)
	ds_read_b32 v104, v4 offset:0
	ds_read_b32 v105, v4 offset:132
	ds_read_b32 v106, v4 offset:264
	ds_read_b32 v107, v4 offset:396
	ds_read_b32 v108, v4 offset:528
	ds_read_b32 v109, v4 offset:660
	ds_read_b32 v110, v4 offset:792
	ds_read_b32 v111, v4 offset:924
	ds_read_b32 v112, v4 offset:32
	ds_read_b32 v113, v4 offset:164
	ds_read_b32 v114, v4 offset:296
	ds_read_b32 v115, v4 offset:428
	ds_read_b32 v116, v4 offset:560
	ds_read_b32 v117, v4 offset:692
	ds_read_b32 v118, v4 offset:824
	ds_read_b32 v119, v4 offset:956
	s_waitcnt lgkmcnt(8)
	v_cvt_pk_bf16_f32 v136, v104, v105
	v_cvt_pk_bf16_f32 v137, v106, v107
	v_cvt_pk_bf16_f32 v138, v108, v109
	v_cvt_pk_bf16_f32 v139, v110, v111
	global_store_dwordx4 v6, v[136:139], s[32:33] nt
	s_add_u32 s32, s32, s49
	s_addc_u32 s33, s33, 0
	ds_read_b32 v120, v4 offset:64
	ds_read_b32 v121, v4 offset:196
	ds_read_b32 v122, v4 offset:328
	ds_read_b32 v123, v4 offset:460
	ds_read_b32 v124, v4 offset:592
	ds_read_b32 v125, v4 offset:724
	ds_read_b32 v126, v4 offset:856
	ds_read_b32 v127, v4 offset:988
	s_waitcnt lgkmcnt(8)
	v_cvt_pk_bf16_f32 v140, v112, v113
	v_cvt_pk_bf16_f32 v141, v114, v115
	v_cvt_pk_bf16_f32 v142, v116, v117
	v_cvt_pk_bf16_f32 v143, v118, v119
	global_store_dwordx4 v6, v[140:143], s[32:33] nt
	s_add_u32 s32, s32, s49
	s_addc_u32 s33, s33, 0
	ds_read_b32 v128, v4 offset:96
	ds_read_b32 v129, v4 offset:228
	ds_read_b32 v130, v4 offset:360
	ds_read_b32 v131, v4 offset:492
	ds_read_b32 v132, v4 offset:624
	ds_read_b32 v133, v4 offset:756
	ds_read_b32 v134, v4 offset:888
	ds_read_b32 v135, v4 offset:1020
	s_waitcnt lgkmcnt(8)
	v_cvt_pk_bf16_f32 v136, v120, v121
	v_cvt_pk_bf16_f32 v137, v122, v123
	v_cvt_pk_bf16_f32 v138, v124, v125
	v_cvt_pk_bf16_f32 v139, v126, v127
	global_store_dwordx4 v6, v[136:139], s[32:33] nt
	s_add_u32 s32, s32, s49
	s_addc_u32 s33, s33, 0
	s_waitcnt lgkmcnt(0)
	v_cvt_pk_bf16_f32 v140, v128, v129
	v_cvt_pk_bf16_f32 v141, v130, v131
	v_cvt_pk_bf16_f32 v142, v132, v133
	v_cvt_pk_bf16_f32 v143, v134, v135
	global_store_dwordx4 v6, v[140:143], s[32:33] nt
	s_add_u32 s32, s32, s49
	s_addc_u32 s33, s33, 0
	s_cmp_ge_u32 s20, 16384
	s_cbranch_scc1 .Ltp0_dr6
	s_cmp_lt_u32 s20, 8192
	s_cbranch_scc1 .Ltp0_r7_s0
	s_cmp_lt_u32 s20, 10240
	s_cbranch_scc1 .Ltp0_r7_s1
	s_sub_u32 s25, s20, 10240
	s_and_b32 s41, s25, 7
	s_lshr_b32 s25, s25, 3
	s_mul_i32 s27, s25, 0xaaab
	s_lshr_b32 s27, s27, 23
	s_mul_i32 s31, s27, 192
	s_sub_u32 s31, s25, s31
	s_lshl_b32 s27, s27, 3
	s_add_u32 s27, s27, s41
	s_mul_i32 s35, s27, 0x180000
	s_lshl_b32 s41, s31, 7
	s_add_u32 s35, s35, s41
	s_add_u32 s0, s70, s35
	s_addc_u32 s1, s71, 0
	s_lshl_b32 s35, s31, 5
	s_mov_b32 s45, 0
	s_cmp_ge_u32 s31, 128
	s_cbranch_scc1 .Ltp0_r7_np
	s_and_b32 s41, s35, 32
	s_lshl_b32 s41, s41, 1
	s_and_b32 s45, s35, 64
	s_lshr_b32 s45, s45, 4
	s_add_u32 s41, s41, s45
	s_andn2_b32 s35, s35, 0x7f
	s_add_u32 s35, s35, s41
	s_mov_b32 s45, 1

.LBB0_363:
	s_waitcnt vmcnt(0)
	s_barrier
	s_cmp_lg_u32 s87, 0x100
	s_cbranch_scc1 .Ltt2_0_done
	s_cmp_lt_u32 s96, 128
	s_cbranch_scc1 .Ltt2_0_done
	s_cmp_ge_u32 s96, 256
	s_cbranch_scc1 .Ltt2_0_done
	s_sub_u32 s20, s96, 128
	s_lshl_b32 s20, s20, 3
	s_add_u32 s20, s20, s93
	s_movk_i32 s23, 1024
	v_mbcnt_hi_u32_b32 v0, -1, v212
	v_and_b32_e32 v0, 63, v0
	v_lshrrev_b32_e32 v1, 3, v0
	v_and_b32_e32 v2, 7, v0
	s_lshl_b32 s25, s93, 14
	v_mul_u32_u24_e32 v3, 0x84, v1
	v_mul_u32_u24_e32 v4, 0x420, v2
	v_lshlrev_b32_e32 v2, 4, v2
	v_add3_u32 v3, v3, v2, s25
	v_lshl_add_u32 v4, v1, 2, v4
	v_add_u32_e32 v4, s25, v4
	v_and_b32_e32 v7, 4, v1
	v_and_b32_e32 v5, 3, v1
	v_lshl_add_u32 v7, v7, 1, v5
	v_readlane_b32 s62, v245, 0
	v_readlane_b32 s63, v245, 1
	s_add_u32 s64, s76, 0x4989000
	s_addc_u32 s65, s77, 0
	v_readlane_b32 s66, v244, 21
	v_readlane_b32 s67, v244, 22
	s_add_u32 s68, s76, 0x8989000
	s_addc_u32 s69, s77, 0
	s_cmp_ge_u32 s20, 12288
	s_cbranch_scc1 .Ltt2_0_done
	s_cmp_lt_u32 s20, 8192
	s_cbranch_scc1 .Ltt2_0_r1_s0
	s_sub_u32 s25, s20, 8192
	s_and_b32 s41, s25, 7
	s_lshr_b32 s25, s25, 3
	s_lshr_b32 s27, s25, 6
	s_and_b32 s31, s25, 63
	s_lshl_b32 s27, s27, 3
	s_add_u32 s27, s27, s41
	s_mul_i32 s35, s27, 0x80000
	s_lshl_b32 s41, s31, 7
	s_add_u32 s35, s35, s41
	s_add_u32 s0, s66, s35
	s_addc_u32 s1, s67, 0
	s_mul_i32 s35, s31, 0x80000
	s_lshl_b32 s41, s27, 7
	s_add_u32 s35, s35, s41
	s_add_u32 s2, s68, s35
	s_addc_u32 s3, s69, 0
	s_mov_b32 s5, 0x2000
	s_mov_b32 s6, 0x10000
	s_mov_b32 s7, 0x4000
	s_branch .Ltt2_0_r1_e
.Ltt2_0_r1_s0:
	s_sub_u32 s25, s20, 0
	s_and_b32 s41, s25, 7
	s_lshr_b32 s25, s25, 3
	s_lshr_b32 s27, s25, 8
	s_and_b32 s31, s25, 255
	s_lshl_b32 s27, s27, 3
	s_add_u32 s27, s27, s41
	s_mul_i32 s35, s27, 0x200000
	s_lshl_b32 s41, s31, 7
	s_add_u32 s35, s35, s41
	s_add_u32 s0, s62, s35
	s_addc_u32 s1, s63, 0
	s_mul_i32 s35, s31, 0x20000
	s_lshl_b32 s41, s27, 7
	s_add_u32 s35, s35, s41
	s_add_u32 s2, s64, s35
	s_addc_u32 s3, s65, 0
	s_mov_b32 s5, 0x8000
	s_mov_b32 s6, 0x40000
	s_mov_b32 s7, 0x1000
.Ltt2_0_r1_e:
	v_mad_u32_u24 v5, v1, s5, v2
	global_load_dwordx4 v[8:11], v5, s[0:1] nt
	s_add_u32 s0, s0, s6
	s_addc_u32 s1, s1, 0
	global_load_dwordx4 v[12:15], v5, s[0:1] nt
	s_add_u32 s0, s0, s6
	s_addc_u32 s1, s1, 0
	global_load_dwordx4 v[16:19], v5, s[0:1] nt
	s_add_u32 s0, s0, s6
	s_addc_u32 s1, s1, 0
	global_load_dwordx4 v[20:23], v5, s[0:1] nt
	s_add_u32 s0, s0, s6
	s_addc_u32 s1, s1, 0
	global_load_dwordx4 v[24:27], v5, s[0:1] nt
	s_add_u32 s0, s0, s6
	s_addc_u32 s1, s1, 0
	global_load_dwordx4 v[28:31], v5, s[0:1] nt
	s_add_u32 s0, s0, s6
	s_addc_u32 s1, s1, 0
	global_load_dwordx4 v[32:35], v5, s[0:1] nt
	s_add_u32 s0, s0, s6
	s_addc_u32 s1, s1, 0
	global_load_dwordx4 v[36:39], v5, s[0:1] nt
	s_add_u32 s0, s0, s6
	s_addc_u32 s1, s1, 0
	s_add_u32 s20, s20, s23
	s_cmp_ge_u32 s20, 12288
	s_cbranch_scc1 .Ltt2_0_dr1
	s_cmp_lt_u32 s20, 8192
	s_cbranch_scc1 .Ltt2_0_r2_s0
	s_sub_u32 s25, s20, 8192
	s_and_b32 s41, s25, 7
	s_lshr_b32 s25, s25, 3
	s_lshr_b32 s27, s25, 6
	s_and_b32 s31, s25, 63
	s_lshl_b32 s27, s27, 3
	s_add_u32 s27, s27, s41
	s_mul_i32 s35, s27, 0x80000
	s_lshl_b32 s41, s31, 7
	s_add_u32 s35, s35, s41
	s_add_u32 s0, s66, s35
	s_addc_u32 s1, s67, 0
	s_mul_i32 s35, s31, 0x80000
	s_lshl_b32 s41, s27, 7
	s_add_u32 s35, s35, s41
	s_add_u32 s10, s68, s35
	s_addc_u32 s11, s69, 0
	s_mov_b32 s5, 0x2000
	s_mov_b32 s6, 0x10000
	s_mov_b32 s47, 0x4000
	s_branch .Ltt2_0_r2_e
.Ltt2_0_r2_s0:
	s_sub_u32 s25, s20, 0
	s_and_b32 s41, s25, 7
	s_lshr_b32 s25, s25, 3
	s_lshr_b32 s27, s25, 8
	s_and_b32 s31, s25, 255
	s_lshl_b32 s27, s27, 3
	s_add_u32 s27, s27, s41
	s_mul_i32 s35, s27, 0x200000
	s_lshl_b32 s41, s31, 7
	s_add_u32 s35, s35, s41
	s_add_u32 s0, s62, s35
	s_addc_u32 s1, s63, 0
	s_mul_i32 s35, s31, 0x20000
	s_lshl_b32 s41, s27, 7
	s_add_u32 s35, s35, s41
	s_add_u32 s10, s64, s35
	s_addc_u32 s11, s65, 0
	s_mov_b32 s5, 0x8000
	s_mov_b32 s6, 0x40000
	s_mov_b32 s47, 0x1000
.Ltt2_0_r2_e:
	v_mad_u32_u24 v5, v1, s5, v2
	global_load_dwordx4 v[40:43], v5, s[0:1] nt
	s_add_u32 s0, s0, s6
	s_addc_u32 s1, s1, 0
	global_load_dwordx4 v[44:47], v5, s[0:1] nt
	s_add_u32 s0, s0, s6
	s_addc_u32 s1, s1, 0
	global_load_dwordx4 v[48:51], v5, s[0:1] nt
	s_add_u32 s0, s0, s6
	s_addc_u32 s1, s1, 0
	global_load_dwordx4 v[52:55], v5, s[0:1] nt
	s_add_u32 s0, s0, s6
	s_addc_u32 s1, s1, 0
	global_load_dwordx4 v[56:59], v5, s[0:1] nt
	s_add_u32 s0, s0, s6
	s_addc_u32 s1, s1, 0
	global_load_dwordx4 v[60:63], v5, s[0:1] nt
	s_add_u32 s0, s0, s6
	s_addc_u32 s1, s1, 0
	global_load_dwordx4 v[64:67], v5, s[0:1] nt
	s_add_u32 s0, s0, s6
	s_addc_u32 s1, s1, 0
	global_load_dwordx4 v[68:71], v5, s[0:1] nt
	s_add_u32 s0, s0, s6
	s_addc_u32 s1, s1, 0
	s_add_u32 s20, s20, s23
	s_cmp_ge_u32 s20, 12288
	s_cbranch_scc1 .Ltt2_0_dr2
	s_cmp_lt_u32 s20, 8192
	s_cbranch_scc1 .Ltt2_0_r3_s0
	s_sub_u32 s25, s20, 8192
	s_and_b32 s41, s25, 7
	s_lshr_b32 s25, s25, 3
	s_lshr_b32 s27, s25, 6
	s_and_b32 s31, s25, 63
	s_lshl_b32 s27, s27, 3
	s_add_u32 s27, s27, s41
	s_mul_i32 s35, s27, 0x80000
	s_lshl_b32 s41, s31, 7
	s_add_u32 s35, s35, s41
	s_add_u32 s0, s66, s35
	s_addc_u32 s1, s67, 0
	s_mul_i32 s35, s31, 0x80000
	s_lshl_b32 s41, s27, 7
	s_add_u32 s35, s35, s41
	s_add_u32 s42, s68, s35
	s_addc_u32 s43, s69, 0
	s_mov_b32 s5, 0x2000
	s_mov_b32 s6, 0x10000
	s_mov_b32 s44, 0x4000
	s_branch .Ltt2_0_r3_e
.Ltt2_0_r3_s0:
	s_sub_u32 s25, s20, 0
	s_and_b32 s41, s25, 7
	s_lshr_b32 s25, s25, 3
	s_lshr_b32 s27, s25, 8
	s_and_b32 s31, s25, 255
	s_lshl_b32 s27, s27, 3
	s_add_u32 s27, s27, s41
	s_mul_i32 s35, s27, 0x200000
	s_lshl_b32 s41, s31, 7
	s_add_u32 s35, s35, s41
	s_add_u32 s0, s62, s35
	s_addc_u32 s1, s63, 0
	s_mul_i32 s35, s31, 0x20000
	s_lshl_b32 s41, s27, 7
	s_add_u32 s35, s35, s41
	s_add_u32 s42, s64, s35
	s_addc_u32 s43, s65, 0
	s_mov_b32 s5, 0x8000
	s_mov_b32 s6, 0x40000
	s_mov_b32 s44, 0x1000
.Ltt2_0_r3_e:
	v_mad_u32_u24 v5, v1, s5, v2
	global_load_dwordx4 v[72:75], v5, s[0:1] nt
	s_add_u32 s0, s0, s6
	s_addc_u32 s1, s1, 0
	global_load_dwordx4 v[76:79], v5, s[0:1] nt
	s_add_u32 s0, s0, s6
	s_addc_u32 s1, s1, 0
	global_load_dwordx4 v[80:83], v5, s[0:1] nt
	s_add_u32 s0, s0, s6
	s_addc_u32 s1, s1, 0
	global_load_dwordx4 v[84:87], v5, s[0:1] nt
	s_add_u32 s0, s0, s6
	s_addc_u32 s1, s1, 0
	global_load_dwordx4 v[88:91], v5, s[0:1] nt
	s_add_u32 s0, s0, s6
	s_addc_u32 s1, s1, 0
	global_load_dwordx4 v[92:95], v5, s[0:1] nt
	s_add_u32 s0, s0, s6
	s_addc_u32 s1, s1, 0
	global_load_dwordx4 v[96:99], v5, s[0:1] nt
	s_add_u32 s0, s0, s6
	s_addc_u32 s1, s1, 0
	global_load_dwordx4 v[100:103], v5, s[0:1] nt
	s_add_u32 s0, s0, s6
	s_addc_u32 s1, s1, 0
	s_add_u32 s20, s20, s23
	s_waitcnt vmcnt(16)
	ds_write_b32 v3, v8 offset:0
	ds_write_b32 v3, v9 offset:4
	ds_write_b32 v3, v10 offset:8
	ds_write_b32 v3, v11 offset:12
	ds_write_b32 v3, v12 offset:1056
	ds_write_b32 v3, v13 offset:1060
	ds_write_b32 v3, v14 offset:1064
	ds_write_b32 v3, v15 offset:1068
	ds_write_b32 v3, v16 offset:2112
	ds_write_b32 v3, v17 offset:2116
	ds_write_b32 v3, v18 offset:2120
	ds_write_b32 v3, v19 offset:2124
	ds_write_b32 v3, v20 offset:3168
	ds_write_b32 v3, v21 offset:3172
	ds_write_b32 v3, v22 offset:3176
	ds_write_b32 v3, v23 offset:3180
	ds_write_b32 v3, v24 offset:4224
	ds_write_b32 v3, v25 offset:4228
	ds_write_b32 v3, v26 offset:4232
	ds_write_b32 v3, v27 offset:4236
	ds_write_b32 v3, v28 offset:5280
	ds_write_b32 v3, v29 offset:5284
	ds_write_b32 v3, v30 offset:5288
	ds_write_b32 v3, v31 offset:5292
	ds_write_b32 v3, v32 offset:6336
	ds_write_b32 v3, v33 offset:6340
	ds_write_b32 v3, v34 offset:6344
	ds_write_b32 v3, v35 offset:6348
	ds_write_b32 v3, v36 offset:7392
	ds_write_b32 v3, v37 offset:7396
	ds_write_b32 v3, v38 offset:7400
	ds_write_b32 v3, v39 offset:7404
	s_mov_b32 s32, s2
	s_mov_b32 s33, s3
	s_lshl_b32 s49, s7, 3
	v_mad_u32_u24 v6, v1, s7, v2
	s_waitcnt lgkmcnt(0)
	ds_read_b32 v104, v4 offset:0
	ds_read_b32 v105, v4 offset:132
	ds_read_b32 v106, v4 offset:264
	ds_read_b32 v107, v4 offset:396
	ds_read_b32 v108, v4 offset:528
	ds_read_b32 v109, v4 offset:660
	ds_read_b32 v110, v4 offset:792
	ds_read_b32 v111, v4 offset:924
	ds_read_b32 v112, v4 offset:32
	ds_read_b32 v113, v4 offset:164
	ds_read_b32 v114, v4 offset:296
	ds_read_b32 v115, v4 offset:428
	ds_read_b32 v116, v4 offset:560
	ds_read_b32 v117, v4 offset:692
	ds_read_b32 v118, v4 offset:824
	ds_read_b32 v119, v4 offset:956
	s_waitcnt lgkmcnt(8)
	v_cvt_pk_bf16_f32 v136, v104, v105
	v_cvt_pk_bf16_f32 v137, v106, v107
	v_cvt_pk_bf16_f32 v138, v108, v109
	v_cvt_pk_bf16_f32 v139, v110, v111
	global_store_dwordx4 v6, v[136:139], s[32:33] nt
	s_add_u32 s32, s32, s49
	s_addc_u32 s33, s33, 0
	ds_read_b32 v120, v4 offset:64
	ds_read_b32 v121, v4 offset:196
	ds_read_b32 v122, v4 offset:328
	ds_read_b32 v123, v4 offset:460
	ds_read_b32 v124, v4 offset:592
	ds_read_b32 v125, v4 offset:724
	ds_read_b32 v126, v4 offset:856
	ds_read_b32 v127, v4 offset:988
	s_waitcnt lgkmcnt(8)
	v_cvt_pk_bf16_f32 v140, v112, v113
	v_cvt_pk_bf16_f32 v141, v114, v115
	v_cvt_pk_bf16_f32 v142, v116, v117
	v_cvt_pk_bf16_f32 v143, v118, v119
	global_store_dwordx4 v6, v[140:143], s[32:33] nt
	s_add_u32 s32, s32, s49
	s_addc_u32 s33, s33, 0
	ds_read_b32 v128, v4 offset:96
	ds_read_b32 v129, v4 offset:228
	ds_read_b32 v130, v4 offset:360
	ds_read_b32 v131, v4 offset:492
	ds_read_b32 v132, v4 offset:624
	ds_read_b32 v133, v4 offset:756
	ds_read_b32 v134, v4 offset:888
	ds_read_b32 v135, v4 offset:1020
	s_waitcnt lgkmcnt(8)
	v_cvt_pk_bf16_f32 v136, v120, v121
	v_cvt_pk_bf16_f32 v137, v122, v123
	v_cvt_pk_bf16_f32 v138, v124, v125
	v_cvt_pk_bf16_f32 v139, v126, v127
	global_store_dwordx4 v6, v[136:139], s[32:33] nt
	s_add_u32 s32, s32, s49
	s_addc_u32 s33, s33, 0
	s_waitcnt lgkmcnt(0)
	v_cvt_pk_bf16_f32 v140, v128, v129
	v_cvt_pk_bf16_f32 v141, v130, v131
	v_cvt_pk_bf16_f32 v142, v132, v133
	v_cvt_pk_bf16_f32 v143, v134, v135
	global_store_dwordx4 v6, v[140:143], s[32:33] nt
	s_add_u32 s32, s32, s49
	s_addc_u32 s33, s33, 0
	s_cmp_ge_u32 s20, 12288
	s_cbranch_scc1 .Ltt2_0_dr3
	s_cmp_lt_u32 s20, 8192
	s_cbranch_scc1 .Ltt2_0_r4_s0
	s_sub_u32 s25, s20, 8192
	s_and_b32 s41, s25, 7
	s_lshr_b32 s25, s25, 3
	s_lshr_b32 s27, s25, 6
	s_and_b32 s31, s25, 63
	s_lshl_b32 s27, s27, 3
	s_add_u32 s27, s27, s41
	s_mul_i32 s35, s27, 0x80000
	s_lshl_b32 s41, s31, 7
	s_add_u32 s35, s35, s41
	s_add_u32 s0, s66, s35
	s_addc_u32 s1, s67, 0
	s_mul_i32 s35, s31, 0x80000
	s_lshl_b32 s41, s27, 7
	s_add_u32 s35, s35, s41
	s_add_u32 s2, s68, s35
	s_addc_u32 s3, s69, 0
	s_mov_b32 s5, 0x2000
	s_mov_b32 s6, 0x10000
	s_mov_b32 s7, 0x4000
	s_branch .Ltt2_0_r4_e

.Ltt2_0_loop:
	s_cmp_ge_u32 s20, 12288
	s_cbranch_scc1 .Ltt2_0_dr4
	s_cmp_lt_u32 s20, 8192
	s_cbranch_scc1 .Ltt2_0_r5_s0
	s_sub_u32 s25, s20, 8192
	s_and_b32 s41, s25, 7
	s_lshr_b32 s25, s25, 3
	s_lshr_b32 s27, s25, 6
	s_and_b32 s31, s25, 63
	s_lshl_b32 s27, s27, 3
	s_add_u32 s27, s27, s41
	s_mul_i32 s35, s27, 0x80000
	s_lshl_b32 s41, s31, 7
	s_add_u32 s35, s35, s41
	s_add_u32 s0, s66, s35
	s_addc_u32 s1, s67, 0
	s_mul_i32 s35, s31, 0x80000
	s_lshl_b32 s41, s27, 7
	s_add_u32 s35, s35, s41
	s_add_u32 s10, s68, s35
	s_addc_u32 s11, s69, 0
	s_mov_b32 s5, 0x2000
	s_mov_b32 s6, 0x10000
	s_mov_b32 s47, 0x4000
	s_branch .Ltt2_0_r5_e

.Ltt2_0_r5_e:
	v_mad_u32_u24 v5, v1, s5, v2
	global_load_dwordx4 v[40:43], v5, s[0:1] nt
	s_add_u32 s0, s0, s6
	s_addc_u32 s1, s1, 0
	global_load_dwordx4 v[44:47], v5, s[0:1] nt
	s_add_u32 s0, s0, s6
	s_addc_u32 s1, s1, 0
	global_load_dwordx4 v[48:51], v5, s[0:1] nt
	s_add_u32 s0, s0, s6
	s_addc_u32 s1, s1, 0
	global_load_dwordx4 v[52:55], v5, s[0:1] nt
	s_add_u32 s0, s0, s6
	s_addc_u32 s1, s1, 0
	global_load_dwordx4 v[56:59], v5, s[0:1] nt
	s_add_u32 s0, s0, s6
	s_addc_u32 s1, s1, 0
	global_load_dwordx4 v[60:63], v5, s[0:1] nt
	s_add_u32 s0, s0, s6
	s_addc_u32 s1, s1, 0
	global_load_dwordx4 v[64:67], v5, s[0:1] nt
	s_add_u32 s0, s0, s6
	s_addc_u32 s1, s1, 0
	global_load_dwordx4 v[68:71], v5, s[0:1] nt
	s_add_u32 s0, s0, s6
	s_addc_u32 s1, s1, 0
	s_add_u32 s20, s20, s23
	s_waitcnt vmcnt(24)
	ds_write_b32 v3, v72 offset:0
	ds_write_b32 v3, v73 offset:4
	ds_write_b32 v3, v74 offset:8
	ds_write_b32 v3, v75 offset:12
	ds_write_b32 v3, v76 offset:1056
	ds_write_b32 v3, v77 offset:1060
	ds_write_b32 v3, v78 offset:1064
	ds_write_b32 v3, v79 offset:1068
	ds_write_b32 v3, v80 offset:2112
	ds_write_b32 v3, v81 offset:2116
	ds_write_b32 v3, v82 offset:2120
	ds_write_b32 v3, v83 offset:2124
	ds_write_b32 v3, v84 offset:3168
	ds_write_b32 v3, v85 offset:3172
	ds_write_b32 v3, v86 offset:3176
	ds_write_b32 v3, v87 offset:3180
	ds_write_b32 v3, v88 offset:4224
	ds_write_b32 v3, v89 offset:4228
	ds_write_b32 v3, v90 offset:4232
	ds_write_b32 v3, v91 offset:4236
	ds_write_b32 v3, v92 offset:5280
	ds_write_b32 v3, v93 offset:5284
	ds_write_b32 v3, v94 offset:5288
	ds_write_b32 v3, v95 offset:5292
	ds_write_b32 v3, v96 offset:6336
	ds_write_b32 v3, v97 offset:6340
	ds_write_b32 v3, v98 offset:6344
	ds_write_b32 v3, v99 offset:6348
	ds_write_b32 v3, v100 offset:7392
	ds_write_b32 v3, v101 offset:7396
	ds_write_b32 v3, v102 offset:7400
	ds_write_b32 v3, v103 offset:7404
	s_mov_b32 s32, s42
	s_mov_b32 s33, s43
	s_lshl_b32 s49, s44, 3
	v_mad_u32_u24 v6, v1, s44, v2
	s_waitcnt lgkmcnt(0)
	ds_read_b32 v104, v4 offset:0
	ds_read_b32 v105, v4 offset:132
	ds_read_b32 v106, v4 offset:264
	ds_read_b32 v107, v4 offset:396
	ds_read_b32 v108, v4 offset:528
	ds_read_b32 v109, v4 offset:660
	ds_read_b32 v110, v4 offset:792
	ds_read_b32 v111, v4 offset:924
	ds_read_b32 v112, v4 offset:32
	ds_read_b32 v113, v4 offset:164
	ds_read_b32 v114, v4 offset:296
	ds_read_b32 v115, v4 offset:428
	ds_read_b32 v116, v4 offset:560
	ds_read_b32 v117, v4 offset:692
	ds_read_b32 v118, v4 offset:824
	ds_read_b32 v119, v4 offset:956
	s_waitcnt lgkmcnt(8)
	v_cvt_pk_bf16_f32 v136, v104, v105
	v_cvt_pk_bf16_f32 v137, v106, v107
	v_cvt_pk_bf16_f32 v138, v108, v109
	v_cvt_pk_bf16_f32 v139, v110, v111
	global_store_dwordx4 v6, v[136:139], s[32:33] nt
	s_add_u32 s32, s32, s49
	s_addc_u32 s33, s33, 0
	ds_read_b32 v120, v4 offset:64
	ds_read_b32 v121, v4 offset:196
	ds_read_b32 v122, v4 offset:328
	ds_read_b32 v123, v4 offset:460
	ds_read_b32 v124, v4 offset:592
	ds_read_b32 v125, v4 offset:724
	ds_read_b32 v126, v4 offset:856
	ds_read_b32 v127, v4 offset:988
	s_waitcnt lgkmcnt(8)
	v_cvt_pk_bf16_f32 v140, v112, v113
	v_cvt_pk_bf16_f32 v141, v114, v115
	v_cvt_pk_bf16_f32 v142, v116, v117
	v_cvt_pk_bf16_f32 v143, v118, v119
	global_store_dwordx4 v6, v[140:143], s[32:33] nt
	s_add_u32 s32, s32, s49
	s_addc_u32 s33, s33, 0
	ds_read_b32 v128, v4 offset:96
	ds_read_b32 v129, v4 offset:228
	ds_read_b32 v130, v4 offset:360
	ds_read_b32 v131, v4 offset:492
	ds_read_b32 v132, v4 offset:624
	ds_read_b32 v133, v4 offset:756
	ds_read_b32 v134, v4 offset:888
	ds_read_b32 v135, v4 offset:1020
	s_waitcnt lgkmcnt(8)
	v_cvt_pk_bf16_f32 v136, v120, v121
	v_cvt_pk_bf16_f32 v137, v122, v123
	v_cvt_pk_bf16_f32 v138, v124, v125
	v_cvt_pk_bf16_f32 v139, v126, v127
	global_store_dwordx4 v6, v[136:139], s[32:33] nt
	s_add_u32 s32, s32, s49
	s_addc_u32 s33, s33, 0
	s_waitcnt lgkmcnt(0)
	v_cvt_pk_bf16_f32 v140, v128, v129
	v_cvt_pk_bf16_f32 v141, v130, v131
	v_cvt_pk_bf16_f32 v142, v132, v133
	v_cvt_pk_bf16_f32 v143, v134, v135
	global_store_dwordx4 v6, v[140:143], s[32:33] nt
	s_add_u32 s32, s32, s49
	s_addc_u32 s33, s33, 0
	s_cmp_ge_u32 s20, 12288
	s_cbranch_scc1 .Ltt2_0_dr5
	s_cmp_lt_u32 s20, 8192
	s_cbranch_scc1 .Ltt2_0_r6_s0
	s_sub_u32 s25, s20, 8192
	s_and_b32 s41, s25, 7
	s_lshr_b32 s25, s25, 3
	s_lshr_b32 s27, s25, 6
	s_and_b32 s31, s25, 63
	s_lshl_b32 s27, s27, 3
	s_add_u32 s27, s27, s41
	s_mul_i32 s35, s27, 0x80000
	s_lshl_b32 s41, s31, 7
	s_add_u32 s35, s35, s41
	s_add_u32 s0, s66, s35
	s_addc_u32 s1, s67, 0
	s_mul_i32 s35, s31, 0x80000
	s_lshl_b32 s41, s27, 7
	s_add_u32 s35, s35, s41
	s_add_u32 s42, s68, s35
	s_addc_u32 s43, s69, 0
	s_mov_b32 s5, 0x2000
	s_mov_b32 s6, 0x10000
	s_mov_b32 s44, 0x4000
	s_branch .Ltt2_0_r6_e

.Ltt2_0_r6_e:
	v_mad_u32_u24 v5, v1, s5, v2
	global_load_dwordx4 v[72:75], v5, s[0:1] nt
	s_add_u32 s0, s0, s6
	s_addc_u32 s1, s1, 0
	global_load_dwordx4 v[76:79], v5, s[0:1] nt
	s_add_u32 s0, s0, s6
	s_addc_u32 s1, s1, 0
	global_load_dwordx4 v[80:83], v5, s[0:1] nt
	s_add_u32 s0, s0, s6
	s_addc_u32 s1, s1, 0
	global_load_dwordx4 v[84:87], v5, s[0:1] nt
	s_add_u32 s0, s0, s6
	s_addc_u32 s1, s1, 0
	global_load_dwordx4 v[88:91], v5, s[0:1] nt
	s_add_u32 s0, s0, s6
	s_addc_u32 s1, s1, 0
	global_load_dwordx4 v[92:95], v5, s[0:1] nt
	s_add_u32 s0, s0, s6
	s_addc_u32 s1, s1, 0
	global_load_dwordx4 v[96:99], v5, s[0:1] nt
	s_add_u32 s0, s0, s6
	s_addc_u32 s1, s1, 0
	global_load_dwordx4 v[100:103], v5, s[0:1] nt
	s_add_u32 s0, s0, s6
	s_addc_u32 s1, s1, 0
	s_add_u32 s20, s20, s23
	s_waitcnt vmcnt(24)
	ds_write_b32 v3, v8 offset:0
	ds_write_b32 v3, v9 offset:4
	ds_write_b32 v3, v10 offset:8
	ds_write_b32 v3, v11 offset:12
	ds_write_b32 v3, v12 offset:1056
	ds_write_b32 v3, v13 offset:1060
	ds_write_b32 v3, v14 offset:1064
	ds_write_b32 v3, v15 offset:1068
	ds_write_b32 v3, v16 offset:2112
	ds_write_b32 v3, v17 offset:2116
	ds_write_b32 v3, v18 offset:2120
	ds_write_b32 v3, v19 offset:2124
	ds_write_b32 v3, v20 offset:3168
	ds_write_b32 v3, v21 offset:3172
	ds_write_b32 v3, v22 offset:3176
	ds_write_b32 v3, v23 offset:3180
	ds_write_b32 v3, v24 offset:4224
	ds_write_b32 v3, v25 offset:4228
	ds_write_b32 v3, v26 offset:4232
	ds_write_b32 v3, v27 offset:4236
	ds_write_b32 v3, v28 offset:5280
	ds_write_b32 v3, v29 offset:5284
	ds_write_b32 v3, v30 offset:5288
	ds_write_b32 v3, v31 offset:5292
	ds_write_b32 v3, v32 offset:6336
	ds_write_b32 v3, v33 offset:6340
	ds_write_b32 v3, v34 offset:6344
	ds_write_b32 v3, v35 offset:6348
	ds_write_b32 v3, v36 offset:7392
	ds_write_b32 v3, v37 offset:7396
	ds_write_b32 v3, v38 offset:7400
	ds_write_b32 v3, v39 offset:7404
	s_mov_b32 s32, s2
	s_mov_b32 s33, s3
	s_lshl_b32 s49, s7, 3
	v_mad_u32_u24 v6, v1, s7, v2
	s_waitcnt lgkmcnt(0)
	ds_read_b32 v104, v4 offset:0
	ds_read_b32 v105, v4 offset:132
	ds_read_b32 v106, v4 offset:264
	ds_read_b32 v107, v4 offset:396
	ds_read_b32 v108, v4 offset:528
	ds_read_b32 v109, v4 offset:660
	ds_read_b32 v110, v4 offset:792
	ds_read_b32 v111, v4 offset:924
	ds_read_b32 v112, v4 offset:32
	ds_read_b32 v113, v4 offset:164
	ds_read_b32 v114, v4 offset:296
	ds_read_b32 v115, v4 offset:428
	ds_read_b32 v116, v4 offset:560
	ds_read_b32 v117, v4 offset:692
	ds_read_b32 v118, v4 offset:824
	ds_read_b32 v119, v4 offset:956
	s_waitcnt lgkmcnt(8)
	v_cvt_pk_bf16_f32 v136, v104, v105
	v_cvt_pk_bf16_f32 v137, v106, v107
	v_cvt_pk_bf16_f32 v138, v108, v109
	v_cvt_pk_bf16_f32 v139, v110, v111
	global_store_dwordx4 v6, v[136:139], s[32:33] nt
	s_add_u32 s32, s32, s49
	s_addc_u32 s33, s33, 0
	ds_read_b32 v120, v4 offset:64
	ds_read_b32 v121, v4 offset:196
	ds_read_b32 v122, v4 offset:328
	ds_read_b32 v123, v4 offset:460
	ds_read_b32 v124, v4 offset:592
	ds_read_b32 v125, v4 offset:724
	ds_read_b32 v126, v4 offset:856
	ds_read_b32 v127, v4 offset:988
	s_waitcnt lgkmcnt(8)
	v_cvt_pk_bf16_f32 v140, v112, v113
	v_cvt_pk_bf16_f32 v141, v114, v115
	v_cvt_pk_bf16_f32 v142, v116, v117
	v_cvt_pk_bf16_f32 v143, v118, v119
	global_store_dwordx4 v6, v[140:143], s[32:33] nt
	s_add_u32 s32, s32, s49
	s_addc_u32 s33, s33, 0
	ds_read_b32 v128, v4 offset:96
	ds_read_b32 v129, v4 offset:228
	ds_read_b32 v130, v4 offset:360
	ds_read_b32 v131, v4 offset:492
	ds_read_b32 v132, v4 offset:624
	ds_read_b32 v133, v4 offset:756
	ds_read_b32 v134, v4 offset:888
	ds_read_b32 v135, v4 offset:1020
	s_waitcnt lgkmcnt(8)
	v_cvt_pk_bf16_f32 v136, v120, v121
	v_cvt_pk_bf16_f32 v137, v122, v123
	v_cvt_pk_bf16_f32 v138, v124, v125
	v_cvt_pk_bf16_f32 v139, v126, v127
	global_store_dwordx4 v6, v[136:139], s[32:33] nt
	s_add_u32 s32, s32, s49
	s_addc_u32 s33, s33, 0
	s_waitcnt lgkmcnt(0)
	v_cvt_pk_bf16_f32 v140, v128, v129
	v_cvt_pk_bf16_f32 v141, v130, v131
	v_cvt_pk_bf16_f32 v142, v132, v133
	v_cvt_pk_bf16_f32 v143, v134, v135
	global_store_dwordx4 v6, v[140:143], s[32:33] nt
	s_add_u32 s32, s32, s49
	s_addc_u32 s33, s33, 0
	s_cmp_ge_u32 s20, 12288
	s_cbranch_scc1 .Ltt2_0_dr6
	s_cmp_lt_u32 s20, 8192
	s_cbranch_scc1 .Ltt2_0_r7_s0
	s_sub_u32 s25, s20, 8192
	s_and_b32 s41, s25, 7
	s_lshr_b32 s25, s25, 3
	s_lshr_b32 s27, s25, 6
	s_and_b32 s31, s25, 63
	s_lshl_b32 s27, s27, 3
	s_add_u32 s27, s27, s41
	s_mul_i32 s35, s27, 0x80000
	s_lshl_b32 s41, s31, 7
	s_add_u32 s35, s35, s41
	s_add_u32 s0, s66, s35
	s_addc_u32 s1, s67, 0
	s_mul_i32 s35, s31, 0x80000
	s_lshl_b32 s41, s27, 7
	s_add_u32 s35, s35, s41
	s_add_u32 s2, s68, s35
	s_addc_u32 s3, s69, 0
	s_mov_b32 s5, 0x2000
	s_mov_b32 s6, 0x10000
	s_mov_b32 s7, 0x4000
	s_branch .Ltt2_0_r7_e

.LBB0_832:
	s_waitcnt vmcnt(0)
	s_barrier
	s_cmp_lg_u32 s87, 0x100
	s_cbranch_scc1 .Ltt7_0_done
	s_cmp_lt_u32 s96, 128
	s_cbranch_scc1 .Ltt7_0_done
	s_cmp_ge_u32 s96, 256
	s_cbranch_scc1 .Ltt7_0_done
	s_sub_u32 s20, s96, 128
	s_lshl_b32 s20, s20, 3
	s_add_u32 s20, s20, s93
	s_movk_i32 s23, 1024
	v_mbcnt_hi_u32_b32 v0, -1, v212
	v_and_b32_e32 v0, 63, v0
	v_lshrrev_b32_e32 v1, 3, v0
	v_and_b32_e32 v2, 7, v0
	s_lshl_b32 s25, s93, 14
	v_mul_u32_u24_e32 v3, 0x84, v1
	v_mul_u32_u24_e32 v4, 0x420, v2
	v_lshlrev_b32_e32 v2, 4, v2
	v_add3_u32 v3, v3, v2, s25
	v_lshl_add_u32 v4, v1, 2, v4
	v_add_u32_e32 v4, s25, v4
	v_and_b32_e32 v7, 4, v1
	v_and_b32_e32 v5, 3, v1
	v_lshl_add_u32 v7, v7, 1, v5
	v_readlane_b32 s62, v244, 21
	v_readlane_b32 s63, v244, 22
	s_add_u32 s64, s76, 0x8989000
	s_addc_u32 s65, s77, 0
	v_readlane_b32 s66, v245, 0
	v_readlane_b32 s67, v245, 1
	s_add_u32 s68, s76, 0x6989000
	s_addc_u32 s69, s77, 0
	s_nop 0
	s_add_u32 s66, s66, 0x4000000
	s_addc_u32 s67, s67, 0
	s_cmp_ge_u32 s20, 12288
	s_cbranch_scc1 .Ltt7_0_done
	s_cmp_lt_u32 s20, 4096
	s_cbranch_scc1 .Ltt7_0_r1_s0
	s_sub_u32 s25, s20, 4096
	s_and_b32 s41, s25, 7
	s_lshr_b32 s25, s25, 3
	s_lshr_b32 s27, s25, 8
	s_and_b32 s31, s25, 255
	s_lshl_b32 s27, s27, 3
	s_add_u32 s27, s27, s41
	s_mul_i32 s35, s27, 0x200000
	s_lshl_b32 s41, s31, 7
	s_add_u32 s35, s35, s41
	s_add_u32 s0, s66, s35
	s_addc_u32 s1, s67, 0
	s_mul_i32 s35, s31, 0x20000
	s_lshl_b32 s41, s27, 7
	s_add_u32 s35, s35, s41
	s_add_u32 s2, s68, s35
	s_addc_u32 s3, s69, 0
	s_mov_b32 s5, 0x8000
	s_mov_b32 s6, 0x40000
	s_mov_b32 s7, 0x1000
	s_branch .Ltt7_0_r1_e
.Ltt7_0_r1_s0:
	s_sub_u32 s25, s20, -4096
	s_and_b32 s41, s25, 7
	s_lshr_b32 s25, s25, 3
	s_lshr_b32 s27, s25, 6
	s_and_b32 s31, s25, 63
	s_lshl_b32 s27, s27, 3
	s_add_u32 s27, s27, s41
	s_mul_i32 s35, s27, 0x80000
	s_lshl_b32 s41, s31, 7
	s_add_u32 s35, s35, s41
	s_add_u32 s0, s62, s35
	s_addc_u32 s1, s63, 0
	s_mul_i32 s35, s31, 0x80000
	s_lshl_b32 s41, s27, 7
	s_add_u32 s35, s35, s41
	s_add_u32 s2, s64, s35
	s_addc_u32 s3, s65, 0
	s_mov_b32 s5, 0x2000
	s_mov_b32 s6, 0x10000
	s_mov_b32 s7, 0x4000
.Ltt7_0_r1_e:
	v_mad_u32_u24 v5, v1, s5, v2
	global_load_dwordx4 v[8:11], v5, s[0:1] nt
	s_add_u32 s0, s0, s6
	s_addc_u32 s1, s1, 0
	global_load_dwordx4 v[12:15], v5, s[0:1] nt
	s_add_u32 s0, s0, s6
	s_addc_u32 s1, s1, 0
	global_load_dwordx4 v[16:19], v5, s[0:1] nt
	s_add_u32 s0, s0, s6
	s_addc_u32 s1, s1, 0
	global_load_dwordx4 v[20:23], v5, s[0:1] nt
	s_add_u32 s0, s0, s6
	s_addc_u32 s1, s1, 0
	global_load_dwordx4 v[24:27], v5, s[0:1] nt
	s_add_u32 s0, s0, s6
	s_addc_u32 s1, s1, 0
	global_load_dwordx4 v[28:31], v5, s[0:1] nt
	s_add_u32 s0, s0, s6
	s_addc_u32 s1, s1, 0
	global_load_dwordx4 v[32:35], v5, s[0:1] nt
	s_add_u32 s0, s0, s6
	s_addc_u32 s1, s1, 0
	global_load_dwordx4 v[36:39], v5, s[0:1] nt
	s_add_u32 s0, s0, s6
	s_addc_u32 s1, s1, 0
	s_add_u32 s20, s20, s23
	s_cmp_ge_u32 s20, 12288
	s_cbranch_scc1 .Ltt7_0_dr1
	s_cmp_lt_u32 s20, 4096
	s_cbranch_scc1 .Ltt7_0_r2_s0
	s_sub_u32 s25, s20, 4096
	s_and_b32 s41, s25, 7
	s_lshr_b32 s25, s25, 3
	s_lshr_b32 s27, s25, 8
	s_and_b32 s31, s25, 255
	s_lshl_b32 s27, s27, 3
	s_add_u32 s27, s27, s41
	s_mul_i32 s35, s27, 0x200000
	s_lshl_b32 s41, s31, 7
	s_add_u32 s35, s35, s41
	s_add_u32 s0, s66, s35
	s_addc_u32 s1, s67, 0
	s_mul_i32 s35, s31, 0x20000
	s_lshl_b32 s41, s27, 7
	s_add_u32 s35, s35, s41
	s_add_u32 s10, s68, s35
	s_addc_u32 s11, s69, 0
	s_mov_b32 s5, 0x8000
	s_mov_b32 s6, 0x40000
	s_mov_b32 s47, 0x1000
	s_branch .Ltt7_0_r2_e
.Ltt7_0_r2_s0:
	s_sub_u32 s25, s20, -4096
	s_and_b32 s41, s25, 7
	s_lshr_b32 s25, s25, 3
	s_lshr_b32 s27, s25, 6
	s_and_b32 s31, s25, 63
	s_lshl_b32 s27, s27, 3
	s_add_u32 s27, s27, s41
	s_mul_i32 s35, s27, 0x80000
	s_lshl_b32 s41, s31, 7
	s_add_u32 s35, s35, s41
	s_add_u32 s0, s62, s35
	s_addc_u32 s1, s63, 0
	s_mul_i32 s35, s31, 0x80000
	s_lshl_b32 s41, s27, 7
	s_add_u32 s35, s35, s41
	s_add_u32 s10, s64, s35
	s_addc_u32 s11, s65, 0
	s_mov_b32 s5, 0x2000
	s_mov_b32 s6, 0x10000
	s_mov_b32 s47, 0x4000
.Ltt7_0_r2_e:
	v_mad_u32_u24 v5, v1, s5, v2
	global_load_dwordx4 v[40:43], v5, s[0:1] nt
	s_add_u32 s0, s0, s6
	s_addc_u32 s1, s1, 0
	global_load_dwordx4 v[44:47], v5, s[0:1] nt
	s_add_u32 s0, s0, s6
	s_addc_u32 s1, s1, 0
	global_load_dwordx4 v[48:51], v5, s[0:1] nt
	s_add_u32 s0, s0, s6
	s_addc_u32 s1, s1, 0
	global_load_dwordx4 v[52:55], v5, s[0:1] nt
	s_add_u32 s0, s0, s6
	s_addc_u32 s1, s1, 0
	global_load_dwordx4 v[56:59], v5, s[0:1] nt
	s_add_u32 s0, s0, s6
	s_addc_u32 s1, s1, 0
	global_load_dwordx4 v[60:63], v5, s[0:1] nt
	s_add_u32 s0, s0, s6
	s_addc_u32 s1, s1, 0
	global_load_dwordx4 v[64:67], v5, s[0:1] nt
	s_add_u32 s0, s0, s6
	s_addc_u32 s1, s1, 0
	global_load_dwordx4 v[68:71], v5, s[0:1] nt
	s_add_u32 s0, s0, s6
	s_addc_u32 s1, s1, 0
	s_add_u32 s20, s20, s23
	s_cmp_ge_u32 s20, 12288
	s_cbranch_scc1 .Ltt7_0_dr2
	s_cmp_lt_u32 s20, 4096
	s_cbranch_scc1 .Ltt7_0_r3_s0
	s_sub_u32 s25, s20, 4096
	s_and_b32 s41, s25, 7
	s_lshr_b32 s25, s25, 3
	s_lshr_b32 s27, s25, 8
	s_and_b32 s31, s25, 255
	s_lshl_b32 s27, s27, 3
	s_add_u32 s27, s27, s41
	s_mul_i32 s35, s27, 0x200000
	s_lshl_b32 s41, s31, 7
	s_add_u32 s35, s35, s41
	s_add_u32 s0, s66, s35
	s_addc_u32 s1, s67, 0
	s_mul_i32 s35, s31, 0x20000
	s_lshl_b32 s41, s27, 7
	s_add_u32 s35, s35, s41
	s_add_u32 s42, s68, s35
	s_addc_u32 s43, s69, 0
	s_mov_b32 s5, 0x8000
	s_mov_b32 s6, 0x40000
	s_mov_b32 s44, 0x1000
	s_branch .Ltt7_0_r3_e
.Ltt7_0_r3_s0:
	s_sub_u32 s25, s20, -4096
	s_and_b32 s41, s25, 7
	s_lshr_b32 s25, s25, 3
	s_lshr_b32 s27, s25, 6
	s_and_b32 s31, s25, 63
	s_lshl_b32 s27, s27, 3
	s_add_u32 s27, s27, s41
	s_mul_i32 s35, s27, 0x80000
	s_lshl_b32 s41, s31, 7
	s_add_u32 s35, s35, s41
	s_add_u32 s0, s62, s35
	s_addc_u32 s1, s63, 0
	s_mul_i32 s35, s31, 0x80000
	s_lshl_b32 s41, s27, 7
	s_add_u32 s35, s35, s41
	s_add_u32 s42, s64, s35
	s_addc_u32 s43, s65, 0
	s_mov_b32 s5, 0x2000
	s_mov_b32 s6, 0x10000
	s_mov_b32 s44, 0x4000
.Ltt7_0_r3_e:
	v_mad_u32_u24 v5, v1, s5, v2
	global_load_dwordx4 v[72:75], v5, s[0:1] nt
	s_add_u32 s0, s0, s6
	s_addc_u32 s1, s1, 0
	global_load_dwordx4 v[76:79], v5, s[0:1] nt
	s_add_u32 s0, s0, s6
	s_addc_u32 s1, s1, 0
	global_load_dwordx4 v[80:83], v5, s[0:1] nt
	s_add_u32 s0, s0, s6
	s_addc_u32 s1, s1, 0
	global_load_dwordx4 v[84:87], v5, s[0:1] nt
	s_add_u32 s0, s0, s6
	s_addc_u32 s1, s1, 0
	global_load_dwordx4 v[88:91], v5, s[0:1] nt
	s_add_u32 s0, s0, s6
	s_addc_u32 s1, s1, 0
	global_load_dwordx4 v[92:95], v5, s[0:1] nt
	s_add_u32 s0, s0, s6
	s_addc_u32 s1, s1, 0
	global_load_dwordx4 v[96:99], v5, s[0:1] nt
	s_add_u32 s0, s0, s6
	s_addc_u32 s1, s1, 0
	global_load_dwordx4 v[100:103], v5, s[0:1] nt
	s_add_u32 s0, s0, s6
	s_addc_u32 s1, s1, 0
	s_add_u32 s20, s20, s23
	s_waitcnt vmcnt(16)
	ds_write_b32 v3, v8 offset:0
	ds_write_b32 v3, v9 offset:4
	ds_write_b32 v3, v10 offset:8
	ds_write_b32 v3, v11 offset:12
	ds_write_b32 v3, v12 offset:1056
	ds_write_b32 v3, v13 offset:1060
	ds_write_b32 v3, v14 offset:1064
	ds_write_b32 v3, v15 offset:1068
	ds_write_b32 v3, v16 offset:2112
	ds_write_b32 v3, v17 offset:2116
	ds_write_b32 v3, v18 offset:2120
	ds_write_b32 v3, v19 offset:2124
	ds_write_b32 v3, v20 offset:3168
	ds_write_b32 v3, v21 offset:3172
	ds_write_b32 v3, v22 offset:3176
	ds_write_b32 v3, v23 offset:3180
	ds_write_b32 v3, v24 offset:4224
	ds_write_b32 v3, v25 offset:4228
	ds_write_b32 v3, v26 offset:4232
	ds_write_b32 v3, v27 offset:4236
	ds_write_b32 v3, v28 offset:5280
	ds_write_b32 v3, v29 offset:5284
	ds_write_b32 v3, v30 offset:5288
	ds_write_b32 v3, v31 offset:5292
	ds_write_b32 v3, v32 offset:6336
	ds_write_b32 v3, v33 offset:6340
	ds_write_b32 v3, v34 offset:6344
	ds_write_b32 v3, v35 offset:6348
	ds_write_b32 v3, v36 offset:7392
	ds_write_b32 v3, v37 offset:7396
	ds_write_b32 v3, v38 offset:7400
	ds_write_b32 v3, v39 offset:7404
	s_mov_b32 s32, s2
	s_mov_b32 s33, s3
	s_lshl_b32 s49, s7, 3
	v_mad_u32_u24 v6, v1, s7, v2
	s_waitcnt lgkmcnt(0)
	ds_read_b32 v104, v4 offset:0
	ds_read_b32 v105, v4 offset:132
	ds_read_b32 v106, v4 offset:264
	ds_read_b32 v107, v4 offset:396
	ds_read_b32 v108, v4 offset:528
	ds_read_b32 v109, v4 offset:660
	ds_read_b32 v110, v4 offset:792
	ds_read_b32 v111, v4 offset:924
	ds_read_b32 v112, v4 offset:32
	ds_read_b32 v113, v4 offset:164
	ds_read_b32 v114, v4 offset:296
	ds_read_b32 v115, v4 offset:428
	ds_read_b32 v116, v4 offset:560
	ds_read_b32 v117, v4 offset:692
	ds_read_b32 v118, v4 offset:824
	ds_read_b32 v119, v4 offset:956
	s_waitcnt lgkmcnt(8)
	v_cvt_pk_bf16_f32 v136, v104, v105
	v_cvt_pk_bf16_f32 v137, v106, v107
	v_cvt_pk_bf16_f32 v138, v108, v109
	v_cvt_pk_bf16_f32 v139, v110, v111
	global_store_dwordx4 v6, v[136:139], s[32:33] nt
	s_add_u32 s32, s32, s49
	s_addc_u32 s33, s33, 0
	ds_read_b32 v120, v4 offset:64
	ds_read_b32 v121, v4 offset:196
	ds_read_b32 v122, v4 offset:328
	ds_read_b32 v123, v4 offset:460
	ds_read_b32 v124, v4 offset:592
	ds_read_b32 v125, v4 offset:724
	ds_read_b32 v126, v4 offset:856
	ds_read_b32 v127, v4 offset:988
	s_waitcnt lgkmcnt(8)
	v_cvt_pk_bf16_f32 v140, v112, v113
	v_cvt_pk_bf16_f32 v141, v114, v115
	v_cvt_pk_bf16_f32 v142, v116, v117
	v_cvt_pk_bf16_f32 v143, v118, v119
	global_store_dwordx4 v6, v[140:143], s[32:33] nt
	s_add_u32 s32, s32, s49
	s_addc_u32 s33, s33, 0
	ds_read_b32 v128, v4 offset:96
	ds_read_b32 v129, v4 offset:228
	ds_read_b32 v130, v4 offset:360
	ds_read_b32 v131, v4 offset:492
	ds_read_b32 v132, v4 offset:624
	ds_read_b32 v133, v4 offset:756
	ds_read_b32 v134, v4 offset:888
	ds_read_b32 v135, v4 offset:1020
	s_waitcnt lgkmcnt(8)
	v_cvt_pk_bf16_f32 v136, v120, v121
	v_cvt_pk_bf16_f32 v137, v122, v123
	v_cvt_pk_bf16_f32 v138, v124, v125
	v_cvt_pk_bf16_f32 v139, v126, v127
	global_store_dwordx4 v6, v[136:139], s[32:33] nt
	s_add_u32 s32, s32, s49
	s_addc_u32 s33, s33, 0
	s_waitcnt lgkmcnt(0)
	v_cvt_pk_bf16_f32 v140, v128, v129
	v_cvt_pk_bf16_f32 v141, v130, v131
	v_cvt_pk_bf16_f32 v142, v132, v133
	v_cvt_pk_bf16_f32 v143, v134, v135
	global_store_dwordx4 v6, v[140:143], s[32:33] nt
	s_add_u32 s32, s32, s49
	s_addc_u32 s33, s33, 0
	s_cmp_ge_u32 s20, 12288
	s_cbranch_scc1 .Ltt7_0_dr3
	s_cmp_lt_u32 s20, 4096
	s_cbranch_scc1 .Ltt7_0_r4_s0
	s_sub_u32 s25, s20, 4096
	s_and_b32 s41, s25, 7
	s_lshr_b32 s25, s25, 3
	s_lshr_b32 s27, s25, 8
	s_and_b32 s31, s25, 255
	s_lshl_b32 s27, s27, 3
	s_add_u32 s27, s27, s41
	s_mul_i32 s35, s27, 0x200000
	s_lshl_b32 s41, s31, 7
	s_add_u32 s35, s35, s41
	s_add_u32 s0, s66, s35
	s_addc_u32 s1, s67, 0
	s_mul_i32 s35, s31, 0x20000
	s_lshl_b32 s41, s27, 7
	s_add_u32 s35, s35, s41
	s_add_u32 s2, s68, s35
	s_addc_u32 s3, s69, 0
	s_mov_b32 s5, 0x8000
	s_mov_b32 s6, 0x40000
	s_mov_b32 s7, 0x1000
	s_branch .Ltt7_0_r4_e

.Ltt7_0_loop:
	s_cmp_ge_u32 s20, 12288
	s_cbranch_scc1 .Ltt7_0_dr4
	s_cmp_lt_u32 s20, 4096
	s_cbranch_scc1 .Ltt7_0_r5_s0
	s_sub_u32 s25, s20, 4096
	s_and_b32 s41, s25, 7
	s_lshr_b32 s25, s25, 3
	s_lshr_b32 s27, s25, 8
	s_and_b32 s31, s25, 255
	s_lshl_b32 s27, s27, 3
	s_add_u32 s27, s27, s41
	s_mul_i32 s35, s27, 0x200000
	s_lshl_b32 s41, s31, 7
	s_add_u32 s35, s35, s41
	s_add_u32 s0, s66, s35
	s_addc_u32 s1, s67, 0
	s_mul_i32 s35, s31, 0x20000
	s_lshl_b32 s41, s27, 7
	s_add_u32 s35, s35, s41
	s_add_u32 s10, s68, s35
	s_addc_u32 s11, s69, 0
	s_mov_b32 s5, 0x8000
	s_mov_b32 s6, 0x40000
	s_mov_b32 s47, 0x1000
	s_branch .Ltt7_0_r5_e

.Ltt7_0_r5_e:
	v_mad_u32_u24 v5, v1, s5, v2
	global_load_dwordx4 v[40:43], v5, s[0:1] nt
	s_add_u32 s0, s0, s6
	s_addc_u32 s1, s1, 0
	global_load_dwordx4 v[44:47], v5, s[0:1] nt
	s_add_u32 s0, s0, s6
	s_addc_u32 s1, s1, 0
	global_load_dwordx4 v[48:51], v5, s[0:1] nt
	s_add_u32 s0, s0, s6
	s_addc_u32 s1, s1, 0
	global_load_dwordx4 v[52:55], v5, s[0:1] nt
	s_add_u32 s0, s0, s6
	s_addc_u32 s1, s1, 0
	global_load_dwordx4 v[56:59], v5, s[0:1] nt
	s_add_u32 s0, s0, s6
	s_addc_u32 s1, s1, 0
	global_load_dwordx4 v[60:63], v5, s[0:1] nt
	s_add_u32 s0, s0, s6
	s_addc_u32 s1, s1, 0
	global_load_dwordx4 v[64:67], v5, s[0:1] nt
	s_add_u32 s0, s0, s6
	s_addc_u32 s1, s1, 0
	global_load_dwordx4 v[68:71], v5, s[0:1] nt
	s_add_u32 s0, s0, s6
	s_addc_u32 s1, s1, 0
	s_add_u32 s20, s20, s23
	s_waitcnt vmcnt(24)
	ds_write_b32 v3, v72 offset:0
	ds_write_b32 v3, v73 offset:4
	ds_write_b32 v3, v74 offset:8
	ds_write_b32 v3, v75 offset:12
	ds_write_b32 v3, v76 offset:1056
	ds_write_b32 v3, v77 offset:1060
	ds_write_b32 v3, v78 offset:1064
	ds_write_b32 v3, v79 offset:1068
	ds_write_b32 v3, v80 offset:2112
	ds_write_b32 v3, v81 offset:2116
	ds_write_b32 v3, v82 offset:2120
	ds_write_b32 v3, v83 offset:2124
	ds_write_b32 v3, v84 offset:3168
	ds_write_b32 v3, v85 offset:3172
	ds_write_b32 v3, v86 offset:3176
	ds_write_b32 v3, v87 offset:3180
	ds_write_b32 v3, v88 offset:4224
	ds_write_b32 v3, v89 offset:4228
	ds_write_b32 v3, v90 offset:4232
	ds_write_b32 v3, v91 offset:4236
	ds_write_b32 v3, v92 offset:5280
	ds_write_b32 v3, v93 offset:5284
	ds_write_b32 v3, v94 offset:5288
	ds_write_b32 v3, v95 offset:5292
	ds_write_b32 v3, v96 offset:6336
	ds_write_b32 v3, v97 offset:6340
	ds_write_b32 v3, v98 offset:6344
	ds_write_b32 v3, v99 offset:6348
	ds_write_b32 v3, v100 offset:7392
	ds_write_b32 v3, v101 offset:7396
	ds_write_b32 v3, v102 offset:7400
	ds_write_b32 v3, v103 offset:7404
	s_mov_b32 s32, s42
	s_mov_b32 s33, s43
	s_lshl_b32 s49, s44, 3
	v_mad_u32_u24 v6, v1, s44, v2
	s_waitcnt lgkmcnt(0)
	ds_read_b32 v104, v4 offset:0
	ds_read_b32 v105, v4 offset:132
	ds_read_b32 v106, v4 offset:264
	ds_read_b32 v107, v4 offset:396
	ds_read_b32 v108, v4 offset:528
	ds_read_b32 v109, v4 offset:660
	ds_read_b32 v110, v4 offset:792
	ds_read_b32 v111, v4 offset:924
	ds_read_b32 v112, v4 offset:32
	ds_read_b32 v113, v4 offset:164
	ds_read_b32 v114, v4 offset:296
	ds_read_b32 v115, v4 offset:428
	ds_read_b32 v116, v4 offset:560
	ds_read_b32 v117, v4 offset:692
	ds_read_b32 v118, v4 offset:824
	ds_read_b32 v119, v4 offset:956
	s_waitcnt lgkmcnt(8)
	v_cvt_pk_bf16_f32 v136, v104, v105
	v_cvt_pk_bf16_f32 v137, v106, v107
	v_cvt_pk_bf16_f32 v138, v108, v109
	v_cvt_pk_bf16_f32 v139, v110, v111
	global_store_dwordx4 v6, v[136:139], s[32:33] nt
	s_add_u32 s32, s32, s49
	s_addc_u32 s33, s33, 0
	ds_read_b32 v120, v4 offset:64
	ds_read_b32 v121, v4 offset:196
	ds_read_b32 v122, v4 offset:328
	ds_read_b32 v123, v4 offset:460
	ds_read_b32 v124, v4 offset:592
	ds_read_b32 v125, v4 offset:724
	ds_read_b32 v126, v4 offset:856
	ds_read_b32 v127, v4 offset:988
	s_waitcnt lgkmcnt(8)
	v_cvt_pk_bf16_f32 v140, v112, v113
	v_cvt_pk_bf16_f32 v141, v114, v115
	v_cvt_pk_bf16_f32 v142, v116, v117
	v_cvt_pk_bf16_f32 v143, v118, v119
	global_store_dwordx4 v6, v[140:143], s[32:33] nt
	s_add_u32 s32, s32, s49
	s_addc_u32 s33, s33, 0
	ds_read_b32 v128, v4 offset:96
	ds_read_b32 v129, v4 offset:228
	ds_read_b32 v130, v4 offset:360
	ds_read_b32 v131, v4 offset:492
	ds_read_b32 v132, v4 offset:624
	ds_read_b32 v133, v4 offset:756
	ds_read_b32 v134, v4 offset:888
	ds_read_b32 v135, v4 offset:1020
	s_waitcnt lgkmcnt(8)
	v_cvt_pk_bf16_f32 v136, v120, v121
	v_cvt_pk_bf16_f32 v137, v122, v123
	v_cvt_pk_bf16_f32 v138, v124, v125
	v_cvt_pk_bf16_f32 v139, v126, v127
	global_store_dwordx4 v6, v[136:139], s[32:33] nt
	s_add_u32 s32, s32, s49
	s_addc_u32 s33, s33, 0
	s_waitcnt lgkmcnt(0)
	v_cvt_pk_bf16_f32 v140, v128, v129
	v_cvt_pk_bf16_f32 v141, v130, v131
	v_cvt_pk_bf16_f32 v142, v132, v133
	v_cvt_pk_bf16_f32 v143, v134, v135
	global_store_dwordx4 v6, v[140:143], s[32:33] nt
	s_add_u32 s32, s32, s49
	s_addc_u32 s33, s33, 0
	s_cmp_ge_u32 s20, 12288
	s_cbranch_scc1 .Ltt7_0_dr5
	s_cmp_lt_u32 s20, 4096
	s_cbranch_scc1 .Ltt7_0_r6_s0
	s_sub_u32 s25, s20, 4096
	s_and_b32 s41, s25, 7
	s_lshr_b32 s25, s25, 3
	s_lshr_b32 s27, s25, 8
	s_and_b32 s31, s25, 255
	s_lshl_b32 s27, s27, 3
	s_add_u32 s27, s27, s41
	s_mul_i32 s35, s27, 0x200000
	s_lshl_b32 s41, s31, 7
	s_add_u32 s35, s35, s41
	s_add_u32 s0, s66, s35
	s_addc_u32 s1, s67, 0
	s_mul_i32 s35, s31, 0x20000
	s_lshl_b32 s41, s27, 7
	s_add_u32 s35, s35, s41
	s_add_u32 s42, s68, s35
	s_addc_u32 s43, s69, 0
	s_mov_b32 s5, 0x8000
	s_mov_b32 s6, 0x40000
	s_mov_b32 s44, 0x1000
	s_branch .Ltt7_0_r6_e

.Ltt7_0_r6_e:
	v_mad_u32_u24 v5, v1, s5, v2
	global_load_dwordx4 v[72:75], v5, s[0:1] nt
	s_add_u32 s0, s0, s6
	s_addc_u32 s1, s1, 0
	global_load_dwordx4 v[76:79], v5, s[0:1] nt
	s_add_u32 s0, s0, s6
	s_addc_u32 s1, s1, 0
	global_load_dwordx4 v[80:83], v5, s[0:1] nt
	s_add_u32 s0, s0, s6
	s_addc_u32 s1, s1, 0
	global_load_dwordx4 v[84:87], v5, s[0:1] nt
	s_add_u32 s0, s0, s6
	s_addc_u32 s1, s1, 0
	global_load_dwordx4 v[88:91], v5, s[0:1] nt
	s_add_u32 s0, s0, s6
	s_addc_u32 s1, s1, 0
	global_load_dwordx4 v[92:95], v5, s[0:1] nt
	s_add_u32 s0, s0, s6
	s_addc_u32 s1, s1, 0
	global_load_dwordx4 v[96:99], v5, s[0:1] nt
	s_add_u32 s0, s0, s6
	s_addc_u32 s1, s1, 0
	global_load_dwordx4 v[100:103], v5, s[0:1] nt
	s_add_u32 s0, s0, s6
	s_addc_u32 s1, s1, 0
	s_add_u32 s20, s20, s23
	s_waitcnt vmcnt(24)
	ds_write_b32 v3, v8 offset:0
	ds_write_b32 v3, v9 offset:4
	ds_write_b32 v3, v10 offset:8
	ds_write_b32 v3, v11 offset:12
	ds_write_b32 v3, v12 offset:1056
	ds_write_b32 v3, v13 offset:1060
	ds_write_b32 v3, v14 offset:1064
	ds_write_b32 v3, v15 offset:1068
	ds_write_b32 v3, v16 offset:2112
	ds_write_b32 v3, v17 offset:2116
	ds_write_b32 v3, v18 offset:2120
	ds_write_b32 v3, v19 offset:2124
	ds_write_b32 v3, v20 offset:3168
	ds_write_b32 v3, v21 offset:3172
	ds_write_b32 v3, v22 offset:3176
	ds_write_b32 v3, v23 offset:3180
	ds_write_b32 v3, v24 offset:4224
	ds_write_b32 v3, v25 offset:4228
	ds_write_b32 v3, v26 offset:4232
	ds_write_b32 v3, v27 offset:4236
	ds_write_b32 v3, v28 offset:5280
	ds_write_b32 v3, v29 offset:5284
	ds_write_b32 v3, v30 offset:5288
	ds_write_b32 v3, v31 offset:5292
	ds_write_b32 v3, v32 offset:6336
	ds_write_b32 v3, v33 offset:6340
	ds_write_b32 v3, v34 offset:6344
	ds_write_b32 v3, v35 offset:6348
	ds_write_b32 v3, v36 offset:7392
	ds_write_b32 v3, v37 offset:7396
	ds_write_b32 v3, v38 offset:7400
	ds_write_b32 v3, v39 offset:7404
	s_mov_b32 s32, s2
	s_mov_b32 s33, s3
	s_lshl_b32 s49, s7, 3
	v_mad_u32_u24 v6, v1, s7, v2
	s_waitcnt lgkmcnt(0)
	ds_read_b32 v104, v4 offset:0
	ds_read_b32 v105, v4 offset:132
	ds_read_b32 v106, v4 offset:264
	ds_read_b32 v107, v4 offset:396
	ds_read_b32 v108, v4 offset:528
	ds_read_b32 v109, v4 offset:660
	ds_read_b32 v110, v4 offset:792
	ds_read_b32 v111, v4 offset:924
	ds_read_b32 v112, v4 offset:32
	ds_read_b32 v113, v4 offset:164
	ds_read_b32 v114, v4 offset:296
	ds_read_b32 v115, v4 offset:428
	ds_read_b32 v116, v4 offset:560
	ds_read_b32 v117, v4 offset:692
	ds_read_b32 v118, v4 offset:824
	ds_read_b32 v119, v4 offset:956
	s_waitcnt lgkmcnt(8)
	v_cvt_pk_bf16_f32 v136, v104, v105
	v_cvt_pk_bf16_f32 v137, v106, v107
	v_cvt_pk_bf16_f32 v138, v108, v109
	v_cvt_pk_bf16_f32 v139, v110, v111
	global_store_dwordx4 v6, v[136:139], s[32:33] nt
	s_add_u32 s32, s32, s49
	s_addc_u32 s33, s33, 0
	ds_read_b32 v120, v4 offset:64
	ds_read_b32 v121, v4 offset:196
	ds_read_b32 v122, v4 offset:328
	ds_read_b32 v123, v4 offset:460
	ds_read_b32 v124, v4 offset:592
	ds_read_b32 v125, v4 offset:724
	ds_read_b32 v126, v4 offset:856
	ds_read_b32 v127, v4 offset:988
	s_waitcnt lgkmcnt(8)
	v_cvt_pk_bf16_f32 v140, v112, v113
	v_cvt_pk_bf16_f32 v141, v114, v115
	v_cvt_pk_bf16_f32 v142, v116, v117
	v_cvt_pk_bf16_f32 v143, v118, v119
	global_store_dwordx4 v6, v[140:143], s[32:33] nt
	s_add_u32 s32, s32, s49
	s_addc_u32 s33, s33, 0
	ds_read_b32 v128, v4 offset:96
	ds_read_b32 v129, v4 offset:228
	ds_read_b32 v130, v4 offset:360
	ds_read_b32 v131, v4 offset:492
	ds_read_b32 v132, v4 offset:624
	ds_read_b32 v133, v4 offset:756
	ds_read_b32 v134, v4 offset:888
	ds_read_b32 v135, v4 offset:1020
	s_waitcnt lgkmcnt(8)
	v_cvt_pk_bf16_f32 v136, v120, v121
	v_cvt_pk_bf16_f32 v137, v122, v123
	v_cvt_pk_bf16_f32 v138, v124, v125
	v_cvt_pk_bf16_f32 v139, v126, v127
	global_store_dwordx4 v6, v[136:139], s[32:33] nt
	s_add_u32 s32, s32, s49
	s_addc_u32 s33, s33, 0
	s_waitcnt lgkmcnt(0)
	v_cvt_pk_bf16_f32 v140, v128, v129
	v_cvt_pk_bf16_f32 v141, v130, v131
	v_cvt_pk_bf16_f32 v142, v132, v133
	v_cvt_pk_bf16_f32 v143, v134, v135
	global_store_dwordx4 v6, v[140:143], s[32:33] nt
	s_add_u32 s32, s32, s49
	s_addc_u32 s33, s33, 0
	s_cmp_ge_u32 s20, 12288
	s_cbranch_scc1 .Ltt7_0_dr6
	s_cmp_lt_u32 s20, 4096
	s_cbranch_scc1 .Ltt7_0_r7_s0
	s_sub_u32 s25, s20, 4096
	s_and_b32 s41, s25, 7
	s_lshr_b32 s25, s25, 3
	s_lshr_b32 s27, s25, 8
	s_and_b32 s31, s25, 255
	s_lshl_b32 s27, s27, 3
	s_add_u32 s27, s27, s41
	s_mul_i32 s35, s27, 0x200000
	s_lshl_b32 s41, s31, 7
	s_add_u32 s35, s35, s41
	s_add_u32 s0, s66, s35
	s_addc_u32 s1, s67, 0
	s_mul_i32 s35, s31, 0x20000
	s_lshl_b32 s41, s27, 7
	s_add_u32 s35, s35, s41
	s_add_u32 s2, s68, s35
	s_addc_u32 s3, s69, 0
	s_mov_b32 s5, 0x8000
	s_mov_b32 s6, 0x40000
	s_mov_b32 s7, 0x1000
	s_branch .Ltt7_0_r7_e

.LBB0_1154:
	s_waitcnt vmcnt(0)
	s_barrier
	s_cmp_lg_u32 s87, 0x100
	s_cbranch_scc1 .Ltt10_0_done
	s_cmp_lt_u32 s96, 96
	s_cbranch_scc1 .Ltt10_0_done
	s_cmp_ge_u32 s96, 256
	s_cbranch_scc1 .Ltt10_0_done
	s_sub_u32 s20, s96, 96
	s_lshl_b32 s20, s20, 3
	s_add_u32 s20, s20, s93
	s_movk_i32 s23, 1280
	v_mbcnt_hi_u32_b32 v0, -1, v212
	v_and_b32_e32 v0, 63, v0
	v_lshrrev_b32_e32 v1, 3, v0
	v_and_b32_e32 v2, 7, v0
	s_lshl_b32 s25, s93, 14
	v_mul_u32_u24_e32 v3, 0x84, v1
	v_mul_u32_u24_e32 v4, 0x420, v2
	v_lshlrev_b32_e32 v2, 4, v2
	v_add3_u32 v3, v3, v2, s25
	v_lshl_add_u32 v4, v1, 2, v4
	v_add_u32_e32 v4, s25, v4
	v_and_b32_e32 v7, 4, v1
	v_and_b32_e32 v5, 3, v1
	v_lshl_add_u32 v7, v7, 1, v5
	v_readlane_b32 s62, v244, 39
	v_readlane_b32 s63, v244, 40
	s_add_u32 s64, s76, 0x4189000
	s_addc_u32 s65, s77, 0
	v_readlane_b32 s66, v244, 21
	v_readlane_b32 s67, v244, 22
	s_add_u32 s68, s76, 0xa989000
	s_addc_u32 s69, s77, 0
	s_nop 0
	s_add_u32 s66, s66, 0x4000000
	s_addc_u32 s67, s67, 0
	s_cmp_ge_u32 s20, 10240
	s_cbranch_scc1 .Ltt10_0_done
	s_cmp_lt_u32 s20, 2048
	s_cbranch_scc1 .Ltt10_0_r1_s0
	s_sub_u32 s25, s20, 2048
	s_and_b32 s41, s25, 7
	s_lshr_b32 s25, s25, 3
	s_lshr_b32 s27, s25, 6
	s_and_b32 s31, s25, 63
	s_lshl_b32 s27, s27, 3
	s_add_u32 s27, s27, s41
	s_mul_i32 s35, s27, 0x80000
	s_lshl_b32 s41, s31, 7
	s_add_u32 s35, s35, s41
	s_add_u32 s0, s66, s35
	s_addc_u32 s1, s67, 0
	s_mul_i32 s35, s31, 0x80000
	s_lshl_b32 s41, s27, 7
	s_add_u32 s35, s35, s41
	s_add_u32 s2, s68, s35
	s_addc_u32 s3, s69, 0
	s_mov_b32 s5, 0x2000
	s_mov_b32 s6, 0x10000
	s_mov_b32 s7, 0x4000
	s_branch .Ltt10_0_r1_e
.Ltt10_0_r1_s0:
	s_sub_u32 s25, s20, 0
	s_and_b32 s41, s25, 7
	s_lshr_b32 s25, s25, 3
	s_lshr_b32 s27, s25, 6
	s_and_b32 s31, s25, 63
	s_lshl_b32 s27, s27, 3
	s_add_u32 s27, s27, s41
	s_mul_i32 s35, s27, 0x80000
	s_lshl_b32 s41, s31, 7
	s_add_u32 s35, s35, s41
	s_add_u32 s0, s62, s35
	s_addc_u32 s1, s63, 0
	s_mul_i32 s35, s31, 0x20000
	s_lshl_b32 s41, s27, 7
	s_add_u32 s35, s35, s41
	s_add_u32 s2, s64, s35
	s_addc_u32 s3, s65, 0
	s_mov_b32 s5, 0x2000
	s_mov_b32 s6, 0x10000
	s_mov_b32 s7, 0x1000
.Ltt10_0_r1_e:
	v_mad_u32_u24 v5, v1, s5, v2
	global_load_dwordx4 v[8:11], v5, s[0:1] nt
	s_add_u32 s0, s0, s6
	s_addc_u32 s1, s1, 0
	global_load_dwordx4 v[12:15], v5, s[0:1] nt
	s_add_u32 s0, s0, s6
	s_addc_u32 s1, s1, 0
	global_load_dwordx4 v[16:19], v5, s[0:1] nt
	s_add_u32 s0, s0, s6
	s_addc_u32 s1, s1, 0
	global_load_dwordx4 v[20:23], v5, s[0:1] nt
	s_add_u32 s0, s0, s6
	s_addc_u32 s1, s1, 0
	global_load_dwordx4 v[24:27], v5, s[0:1] nt
	s_add_u32 s0, s0, s6
	s_addc_u32 s1, s1, 0
	global_load_dwordx4 v[28:31], v5, s[0:1] nt
	s_add_u32 s0, s0, s6
	s_addc_u32 s1, s1, 0
	global_load_dwordx4 v[32:35], v5, s[0:1] nt
	s_add_u32 s0, s0, s6
	s_addc_u32 s1, s1, 0
	global_load_dwordx4 v[36:39], v5, s[0:1] nt
	s_add_u32 s0, s0, s6
	s_addc_u32 s1, s1, 0
	s_add_u32 s20, s20, s23
	s_cmp_ge_u32 s20, 10240
	s_cbranch_scc1 .Ltt10_0_dr1
	s_cmp_lt_u32 s20, 2048
	s_cbranch_scc1 .Ltt10_0_r2_s0
	s_sub_u32 s25, s20, 2048
	s_and_b32 s41, s25, 7
	s_lshr_b32 s25, s25, 3
	s_lshr_b32 s27, s25, 6
	s_and_b32 s31, s25, 63
	s_lshl_b32 s27, s27, 3
	s_add_u32 s27, s27, s41
	s_mul_i32 s35, s27, 0x80000
	s_lshl_b32 s41, s31, 7
	s_add_u32 s35, s35, s41
	s_add_u32 s0, s66, s35
	s_addc_u32 s1, s67, 0
	s_mul_i32 s35, s31, 0x80000
	s_lshl_b32 s41, s27, 7
	s_add_u32 s35, s35, s41
	s_add_u32 s10, s68, s35
	s_addc_u32 s11, s69, 0
	s_mov_b32 s5, 0x2000
	s_mov_b32 s6, 0x10000
	s_mov_b32 s47, 0x4000
	s_branch .Ltt10_0_r2_e
.Ltt10_0_r2_s0:
	s_sub_u32 s25, s20, 0
	s_and_b32 s41, s25, 7
	s_lshr_b32 s25, s25, 3
	s_lshr_b32 s27, s25, 6
	s_and_b32 s31, s25, 63
	s_lshl_b32 s27, s27, 3
	s_add_u32 s27, s27, s41
	s_mul_i32 s35, s27, 0x80000
	s_lshl_b32 s41, s31, 7
	s_add_u32 s35, s35, s41
	s_add_u32 s0, s62, s35
	s_addc_u32 s1, s63, 0
	s_mul_i32 s35, s31, 0x20000
	s_lshl_b32 s41, s27, 7
	s_add_u32 s35, s35, s41
	s_add_u32 s10, s64, s35
	s_addc_u32 s11, s65, 0
	s_mov_b32 s5, 0x2000
	s_mov_b32 s6, 0x10000
	s_mov_b32 s47, 0x1000
.Ltt10_0_r2_e:
	v_mad_u32_u24 v5, v1, s5, v2
	global_load_dwordx4 v[40:43], v5, s[0:1] nt
	s_add_u32 s0, s0, s6
	s_addc_u32 s1, s1, 0
	global_load_dwordx4 v[44:47], v5, s[0:1] nt
	s_add_u32 s0, s0, s6
	s_addc_u32 s1, s1, 0
	global_load_dwordx4 v[48:51], v5, s[0:1] nt
	s_add_u32 s0, s0, s6
	s_addc_u32 s1, s1, 0
	global_load_dwordx4 v[52:55], v5, s[0:1] nt
	s_add_u32 s0, s0, s6
	s_addc_u32 s1, s1, 0
	global_load_dwordx4 v[56:59], v5, s[0:1] nt
	s_add_u32 s0, s0, s6
	s_addc_u32 s1, s1, 0
	global_load_dwordx4 v[60:63], v5, s[0:1] nt
	s_add_u32 s0, s0, s6
	s_addc_u32 s1, s1, 0
	global_load_dwordx4 v[64:67], v5, s[0:1] nt
	s_add_u32 s0, s0, s6
	s_addc_u32 s1, s1, 0
	global_load_dwordx4 v[68:71], v5, s[0:1] nt
	s_add_u32 s0, s0, s6
	s_addc_u32 s1, s1, 0
	s_add_u32 s20, s20, s23
	s_cmp_ge_u32 s20, 10240
	s_cbranch_scc1 .Ltt10_0_dr2
	s_cmp_lt_u32 s20, 2048
	s_cbranch_scc1 .Ltt10_0_r3_s0
	s_sub_u32 s25, s20, 2048
	s_and_b32 s41, s25, 7
	s_lshr_b32 s25, s25, 3
	s_lshr_b32 s27, s25, 6
	s_and_b32 s31, s25, 63
	s_lshl_b32 s27, s27, 3
	s_add_u32 s27, s27, s41
	s_mul_i32 s35, s27, 0x80000
	s_lshl_b32 s41, s31, 7
	s_add_u32 s35, s35, s41
	s_add_u32 s0, s66, s35
	s_addc_u32 s1, s67, 0
	s_mul_i32 s35, s31, 0x80000
	s_lshl_b32 s41, s27, 7
	s_add_u32 s35, s35, s41
	s_add_u32 s42, s68, s35
	s_addc_u32 s43, s69, 0
	s_mov_b32 s5, 0x2000
	s_mov_b32 s6, 0x10000
	s_mov_b32 s44, 0x4000
	s_branch .Ltt10_0_r3_e
.Ltt10_0_r3_s0:
	s_sub_u32 s25, s20, 0
	s_and_b32 s41, s25, 7
	s_lshr_b32 s25, s25, 3
	s_lshr_b32 s27, s25, 6
	s_and_b32 s31, s25, 63
	s_lshl_b32 s27, s27, 3
	s_add_u32 s27, s27, s41
	s_mul_i32 s35, s27, 0x80000
	s_lshl_b32 s41, s31, 7
	s_add_u32 s35, s35, s41
	s_add_u32 s0, s62, s35
	s_addc_u32 s1, s63, 0
	s_mul_i32 s35, s31, 0x20000
	s_lshl_b32 s41, s27, 7
	s_add_u32 s35, s35, s41
	s_add_u32 s42, s64, s35
	s_addc_u32 s43, s65, 0
	s_mov_b32 s5, 0x2000
	s_mov_b32 s6, 0x10000
	s_mov_b32 s44, 0x1000
.Ltt10_0_r3_e:
	v_mad_u32_u24 v5, v1, s5, v2
	global_load_dwordx4 v[72:75], v5, s[0:1] nt
	s_add_u32 s0, s0, s6
	s_addc_u32 s1, s1, 0
	global_load_dwordx4 v[76:79], v5, s[0:1] nt
	s_add_u32 s0, s0, s6
	s_addc_u32 s1, s1, 0
	global_load_dwordx4 v[80:83], v5, s[0:1] nt
	s_add_u32 s0, s0, s6
	s_addc_u32 s1, s1, 0
	global_load_dwordx4 v[84:87], v5, s[0:1] nt
	s_add_u32 s0, s0, s6
	s_addc_u32 s1, s1, 0
	global_load_dwordx4 v[88:91], v5, s[0:1] nt
	s_add_u32 s0, s0, s6
	s_addc_u32 s1, s1, 0
	global_load_dwordx4 v[92:95], v5, s[0:1] nt
	s_add_u32 s0, s0, s6
	s_addc_u32 s1, s1, 0
	global_load_dwordx4 v[96:99], v5, s[0:1] nt
	s_add_u32 s0, s0, s6
	s_addc_u32 s1, s1, 0
	global_load_dwordx4 v[100:103], v5, s[0:1] nt
	s_add_u32 s0, s0, s6
	s_addc_u32 s1, s1, 0
	s_add_u32 s20, s20, s23
	s_waitcnt vmcnt(16)
	ds_write_b32 v3, v8 offset:0
	ds_write_b32 v3, v9 offset:4
	ds_write_b32 v3, v10 offset:8
	ds_write_b32 v3, v11 offset:12
	ds_write_b32 v3, v12 offset:1056
	ds_write_b32 v3, v13 offset:1060
	ds_write_b32 v3, v14 offset:1064
	ds_write_b32 v3, v15 offset:1068
	ds_write_b32 v3, v16 offset:2112
	ds_write_b32 v3, v17 offset:2116
	ds_write_b32 v3, v18 offset:2120
	ds_write_b32 v3, v19 offset:2124
	ds_write_b32 v3, v20 offset:3168
	ds_write_b32 v3, v21 offset:3172
	ds_write_b32 v3, v22 offset:3176
	ds_write_b32 v3, v23 offset:3180
	ds_write_b32 v3, v24 offset:4224
	ds_write_b32 v3, v25 offset:4228
	ds_write_b32 v3, v26 offset:4232
	ds_write_b32 v3, v27 offset:4236
	ds_write_b32 v3, v28 offset:5280
	ds_write_b32 v3, v29 offset:5284
	ds_write_b32 v3, v30 offset:5288
	ds_write_b32 v3, v31 offset:5292
	ds_write_b32 v3, v32 offset:6336
	ds_write_b32 v3, v33 offset:6340
	ds_write_b32 v3, v34 offset:6344
	ds_write_b32 v3, v35 offset:6348
	ds_write_b32 v3, v36 offset:7392
	ds_write_b32 v3, v37 offset:7396
	ds_write_b32 v3, v38 offset:7400
	ds_write_b32 v3, v39 offset:7404
	s_mov_b32 s32, s2
	s_mov_b32 s33, s3
	s_lshl_b32 s49, s7, 3
	v_mad_u32_u24 v6, v1, s7, v2
	s_waitcnt lgkmcnt(0)
	ds_read_b32 v104, v4 offset:0
	ds_read_b32 v105, v4 offset:132
	ds_read_b32 v106, v4 offset:264
	ds_read_b32 v107, v4 offset:396
	ds_read_b32 v108, v4 offset:528
	ds_read_b32 v109, v4 offset:660
	ds_read_b32 v110, v4 offset:792
	ds_read_b32 v111, v4 offset:924
	ds_read_b32 v112, v4 offset:32
	ds_read_b32 v113, v4 offset:164
	ds_read_b32 v114, v4 offset:296
	ds_read_b32 v115, v4 offset:428
	ds_read_b32 v116, v4 offset:560
	ds_read_b32 v117, v4 offset:692
	ds_read_b32 v118, v4 offset:824
	ds_read_b32 v119, v4 offset:956
	s_waitcnt lgkmcnt(8)
	v_cvt_pk_bf16_f32 v136, v104, v105
	v_cvt_pk_bf16_f32 v137, v106, v107
	v_cvt_pk_bf16_f32 v138, v108, v109
	v_cvt_pk_bf16_f32 v139, v110, v111
	global_store_dwordx4 v6, v[136:139], s[32:33] nt
	s_add_u32 s32, s32, s49
	s_addc_u32 s33, s33, 0
	ds_read_b32 v120, v4 offset:64
	ds_read_b32 v121, v4 offset:196
	ds_read_b32 v122, v4 offset:328
	ds_read_b32 v123, v4 offset:460
	ds_read_b32 v124, v4 offset:592
	ds_read_b32 v125, v4 offset:724
	ds_read_b32 v126, v4 offset:856
	ds_read_b32 v127, v4 offset:988
	s_waitcnt lgkmcnt(8)
	v_cvt_pk_bf16_f32 v140, v112, v113
	v_cvt_pk_bf16_f32 v141, v114, v115
	v_cvt_pk_bf16_f32 v142, v116, v117
	v_cvt_pk_bf16_f32 v143, v118, v119
	global_store_dwordx4 v6, v[140:143], s[32:33] nt
	s_add_u32 s32, s32, s49
	s_addc_u32 s33, s33, 0
	ds_read_b32 v128, v4 offset:96
	ds_read_b32 v129, v4 offset:228
	ds_read_b32 v130, v4 offset:360
	ds_read_b32 v131, v4 offset:492
	ds_read_b32 v132, v4 offset:624
	ds_read_b32 v133, v4 offset:756
	ds_read_b32 v134, v4 offset:888
	ds_read_b32 v135, v4 offset:1020
	s_waitcnt lgkmcnt(8)
	v_cvt_pk_bf16_f32 v136, v120, v121
	v_cvt_pk_bf16_f32 v137, v122, v123
	v_cvt_pk_bf16_f32 v138, v124, v125
	v_cvt_pk_bf16_f32 v139, v126, v127
	global_store_dwordx4 v6, v[136:139], s[32:33] nt
	s_add_u32 s32, s32, s49
	s_addc_u32 s33, s33, 0
	s_waitcnt lgkmcnt(0)
	v_cvt_pk_bf16_f32 v140, v128, v129
	v_cvt_pk_bf16_f32 v141, v130, v131
	v_cvt_pk_bf16_f32 v142, v132, v133
	v_cvt_pk_bf16_f32 v143, v134, v135
	global_store_dwordx4 v6, v[140:143], s[32:33] nt
	s_add_u32 s32, s32, s49
	s_addc_u32 s33, s33, 0
	s_cmp_ge_u32 s20, 10240
	s_cbranch_scc1 .Ltt10_0_dr3
	s_cmp_lt_u32 s20, 2048
	s_cbranch_scc1 .Ltt10_0_r4_s0
	s_sub_u32 s25, s20, 2048
	s_and_b32 s41, s25, 7
	s_lshr_b32 s25, s25, 3
	s_lshr_b32 s27, s25, 6
	s_and_b32 s31, s25, 63
	s_lshl_b32 s27, s27, 3
	s_add_u32 s27, s27, s41
	s_mul_i32 s35, s27, 0x80000
	s_lshl_b32 s41, s31, 7
	s_add_u32 s35, s35, s41
	s_add_u32 s0, s66, s35
	s_addc_u32 s1, s67, 0
	s_mul_i32 s35, s31, 0x80000
	s_lshl_b32 s41, s27, 7
	s_add_u32 s35, s35, s41
	s_add_u32 s2, s68, s35
	s_addc_u32 s3, s69, 0
	s_mov_b32 s5, 0x2000
	s_mov_b32 s6, 0x10000
	s_mov_b32 s7, 0x4000
	s_branch .Ltt10_0_r4_e

.Ltt10_0_loop:
	s_cmp_ge_u32 s20, 10240
	s_cbranch_scc1 .Ltt10_0_dr4
	s_cmp_lt_u32 s20, 2048
	s_cbranch_scc1 .Ltt10_0_r5_s0
	s_sub_u32 s25, s20, 2048
	s_and_b32 s41, s25, 7
	s_lshr_b32 s25, s25, 3
	s_lshr_b32 s27, s25, 6
	s_and_b32 s31, s25, 63
	s_lshl_b32 s27, s27, 3
	s_add_u32 s27, s27, s41
	s_mul_i32 s35, s27, 0x80000
	s_lshl_b32 s41, s31, 7
	s_add_u32 s35, s35, s41
	s_add_u32 s0, s66, s35
	s_addc_u32 s1, s67, 0
	s_mul_i32 s35, s31, 0x80000
	s_lshl_b32 s41, s27, 7
	s_add_u32 s35, s35, s41
	s_add_u32 s10, s68, s35
	s_addc_u32 s11, s69, 0
	s_mov_b32 s5, 0x2000
	s_mov_b32 s6, 0x10000
	s_mov_b32 s47, 0x4000
	s_branch .Ltt10_0_r5_e

.Ltt10_0_r5_e:
	v_mad_u32_u24 v5, v1, s5, v2
	global_load_dwordx4 v[40:43], v5, s[0:1] nt
	s_add_u32 s0, s0, s6
	s_addc_u32 s1, s1, 0
	global_load_dwordx4 v[44:47], v5, s[0:1] nt
	s_add_u32 s0, s0, s6
	s_addc_u32 s1, s1, 0
	global_load_dwordx4 v[48:51], v5, s[0:1] nt
	s_add_u32 s0, s0, s6
	s_addc_u32 s1, s1, 0
	global_load_dwordx4 v[52:55], v5, s[0:1] nt
	s_add_u32 s0, s0, s6
	s_addc_u32 s1, s1, 0
	global_load_dwordx4 v[56:59], v5, s[0:1] nt
	s_add_u32 s0, s0, s6
	s_addc_u32 s1, s1, 0
	global_load_dwordx4 v[60:63], v5, s[0:1] nt
	s_add_u32 s0, s0, s6
	s_addc_u32 s1, s1, 0
	global_load_dwordx4 v[64:67], v5, s[0:1] nt
	s_add_u32 s0, s0, s6
	s_addc_u32 s1, s1, 0
	global_load_dwordx4 v[68:71], v5, s[0:1] nt
	s_add_u32 s0, s0, s6
	s_addc_u32 s1, s1, 0
	s_add_u32 s20, s20, s23
	s_waitcnt vmcnt(24)
	ds_write_b32 v3, v72 offset:0
	ds_write_b32 v3, v73 offset:4
	ds_write_b32 v3, v74 offset:8
	ds_write_b32 v3, v75 offset:12
	ds_write_b32 v3, v76 offset:1056
	ds_write_b32 v3, v77 offset:1060
	ds_write_b32 v3, v78 offset:1064
	ds_write_b32 v3, v79 offset:1068
	ds_write_b32 v3, v80 offset:2112
	ds_write_b32 v3, v81 offset:2116
	ds_write_b32 v3, v82 offset:2120
	ds_write_b32 v3, v83 offset:2124
	ds_write_b32 v3, v84 offset:3168
	ds_write_b32 v3, v85 offset:3172
	ds_write_b32 v3, v86 offset:3176
	ds_write_b32 v3, v87 offset:3180
	ds_write_b32 v3, v88 offset:4224
	ds_write_b32 v3, v89 offset:4228
	ds_write_b32 v3, v90 offset:4232
	ds_write_b32 v3, v91 offset:4236
	ds_write_b32 v3, v92 offset:5280
	ds_write_b32 v3, v93 offset:5284
	ds_write_b32 v3, v94 offset:5288
	ds_write_b32 v3, v95 offset:5292
	ds_write_b32 v3, v96 offset:6336
	ds_write_b32 v3, v97 offset:6340
	ds_write_b32 v3, v98 offset:6344
	ds_write_b32 v3, v99 offset:6348
	ds_write_b32 v3, v100 offset:7392
	ds_write_b32 v3, v101 offset:7396
	ds_write_b32 v3, v102 offset:7400
	ds_write_b32 v3, v103 offset:7404
	s_mov_b32 s32, s42
	s_mov_b32 s33, s43
	s_lshl_b32 s49, s44, 3
	v_mad_u32_u24 v6, v1, s44, v2
	s_waitcnt lgkmcnt(0)
	ds_read_b32 v104, v4 offset:0
	ds_read_b32 v105, v4 offset:132
	ds_read_b32 v106, v4 offset:264
	ds_read_b32 v107, v4 offset:396
	ds_read_b32 v108, v4 offset:528
	ds_read_b32 v109, v4 offset:660
	ds_read_b32 v110, v4 offset:792
	ds_read_b32 v111, v4 offset:924
	ds_read_b32 v112, v4 offset:32
	ds_read_b32 v113, v4 offset:164
	ds_read_b32 v114, v4 offset:296
	ds_read_b32 v115, v4 offset:428
	ds_read_b32 v116, v4 offset:560
	ds_read_b32 v117, v4 offset:692
	ds_read_b32 v118, v4 offset:824
	ds_read_b32 v119, v4 offset:956
	s_waitcnt lgkmcnt(8)
	v_cvt_pk_bf16_f32 v136, v104, v105
	v_cvt_pk_bf16_f32 v137, v106, v107
	v_cvt_pk_bf16_f32 v138, v108, v109
	v_cvt_pk_bf16_f32 v139, v110, v111
	global_store_dwordx4 v6, v[136:139], s[32:33] nt
	s_add_u32 s32, s32, s49
	s_addc_u32 s33, s33, 0
	ds_read_b32 v120, v4 offset:64
	ds_read_b32 v121, v4 offset:196
	ds_read_b32 v122, v4 offset:328
	ds_read_b32 v123, v4 offset:460
	ds_read_b32 v124, v4 offset:592
	ds_read_b32 v125, v4 offset:724
	ds_read_b32 v126, v4 offset:856
	ds_read_b32 v127, v4 offset:988
	s_waitcnt lgkmcnt(8)
	v_cvt_pk_bf16_f32 v140, v112, v113
	v_cvt_pk_bf16_f32 v141, v114, v115
	v_cvt_pk_bf16_f32 v142, v116, v117
	v_cvt_pk_bf16_f32 v143, v118, v119
	global_store_dwordx4 v6, v[140:143], s[32:33] nt
	s_add_u32 s32, s32, s49
	s_addc_u32 s33, s33, 0
	ds_read_b32 v128, v4 offset:96
	ds_read_b32 v129, v4 offset:228
	ds_read_b32 v130, v4 offset:360
	ds_read_b32 v131, v4 offset:492
	ds_read_b32 v132, v4 offset:624
	ds_read_b32 v133, v4 offset:756
	ds_read_b32 v134, v4 offset:888
	ds_read_b32 v135, v4 offset:1020
	s_waitcnt lgkmcnt(8)
	v_cvt_pk_bf16_f32 v136, v120, v121
	v_cvt_pk_bf16_f32 v137, v122, v123
	v_cvt_pk_bf16_f32 v138, v124, v125
	v_cvt_pk_bf16_f32 v139, v126, v127
	global_store_dwordx4 v6, v[136:139], s[32:33] nt
	s_add_u32 s32, s32, s49
	s_addc_u32 s33, s33, 0
	s_waitcnt lgkmcnt(0)
	v_cvt_pk_bf16_f32 v140, v128, v129
	v_cvt_pk_bf16_f32 v141, v130, v131
	v_cvt_pk_bf16_f32 v142, v132, v133
	v_cvt_pk_bf16_f32 v143, v134, v135
	global_store_dwordx4 v6, v[140:143], s[32:33] nt
	s_add_u32 s32, s32, s49
	s_addc_u32 s33, s33, 0
	s_cmp_ge_u32 s20, 10240
	s_cbranch_scc1 .Ltt10_0_dr5
	s_cmp_lt_u32 s20, 2048
	s_cbranch_scc1 .Ltt10_0_r6_s0
	s_sub_u32 s25, s20, 2048
	s_and_b32 s41, s25, 7
	s_lshr_b32 s25, s25, 3
	s_lshr_b32 s27, s25, 6
	s_and_b32 s31, s25, 63
	s_lshl_b32 s27, s27, 3
	s_add_u32 s27, s27, s41
	s_mul_i32 s35, s27, 0x80000
	s_lshl_b32 s41, s31, 7
	s_add_u32 s35, s35, s41
	s_add_u32 s0, s66, s35
	s_addc_u32 s1, s67, 0
	s_mul_i32 s35, s31, 0x80000
	s_lshl_b32 s41, s27, 7
	s_add_u32 s35, s35, s41
	s_add_u32 s42, s68, s35
	s_addc_u32 s43, s69, 0
	s_mov_b32 s5, 0x2000
	s_mov_b32 s6, 0x10000
	s_mov_b32 s44, 0x4000
	s_branch .Ltt10_0_r6_e

.Ltt10_0_r6_e:
	v_mad_u32_u24 v5, v1, s5, v2
	global_load_dwordx4 v[72:75], v5, s[0:1] nt
	s_add_u32 s0, s0, s6
	s_addc_u32 s1, s1, 0
	global_load_dwordx4 v[76:79], v5, s[0:1] nt
	s_add_u32 s0, s0, s6
	s_addc_u32 s1, s1, 0
	global_load_dwordx4 v[80:83], v5, s[0:1] nt
	s_add_u32 s0, s0, s6
	s_addc_u32 s1, s1, 0
	global_load_dwordx4 v[84:87], v5, s[0:1] nt
	s_add_u32 s0, s0, s6
	s_addc_u32 s1, s1, 0
	global_load_dwordx4 v[88:91], v5, s[0:1] nt
	s_add_u32 s0, s0, s6
	s_addc_u32 s1, s1, 0
	global_load_dwordx4 v[92:95], v5, s[0:1] nt
	s_add_u32 s0, s0, s6
	s_addc_u32 s1, s1, 0
	global_load_dwordx4 v[96:99], v5, s[0:1] nt
	s_add_u32 s0, s0, s6
	s_addc_u32 s1, s1, 0
	global_load_dwordx4 v[100:103], v5, s[0:1] nt
	s_add_u32 s0, s0, s6
	s_addc_u32 s1, s1, 0
	s_add_u32 s20, s20, s23
	s_waitcnt vmcnt(24)
	ds_write_b32 v3, v8 offset:0
	ds_write_b32 v3, v9 offset:4
	ds_write_b32 v3, v10 offset:8
	ds_write_b32 v3, v11 offset:12
	ds_write_b32 v3, v12 offset:1056
	ds_write_b32 v3, v13 offset:1060
	ds_write_b32 v3, v14 offset:1064
	ds_write_b32 v3, v15 offset:1068
	ds_write_b32 v3, v16 offset:2112
	ds_write_b32 v3, v17 offset:2116
	ds_write_b32 v3, v18 offset:2120
	ds_write_b32 v3, v19 offset:2124
	ds_write_b32 v3, v20 offset:3168
	ds_write_b32 v3, v21 offset:3172
	ds_write_b32 v3, v22 offset:3176
	ds_write_b32 v3, v23 offset:3180
	ds_write_b32 v3, v24 offset:4224
	ds_write_b32 v3, v25 offset:4228
	ds_write_b32 v3, v26 offset:4232
	ds_write_b32 v3, v27 offset:4236
	ds_write_b32 v3, v28 offset:5280
	ds_write_b32 v3, v29 offset:5284
	ds_write_b32 v3, v30 offset:5288
	ds_write_b32 v3, v31 offset:5292
	ds_write_b32 v3, v32 offset:6336
	ds_write_b32 v3, v33 offset:6340
	ds_write_b32 v3, v34 offset:6344
	ds_write_b32 v3, v35 offset:6348
	ds_write_b32 v3, v36 offset:7392
	ds_write_b32 v3, v37 offset:7396
	ds_write_b32 v3, v38 offset:7400
	ds_write_b32 v3, v39 offset:7404
	s_mov_b32 s32, s2
	s_mov_b32 s33, s3
	s_lshl_b32 s49, s7, 3
	v_mad_u32_u24 v6, v1, s7, v2
	s_waitcnt lgkmcnt(0)
	ds_read_b32 v104, v4 offset:0
	ds_read_b32 v105, v4 offset:132
	ds_read_b32 v106, v4 offset:264
	ds_read_b32 v107, v4 offset:396
	ds_read_b32 v108, v4 offset:528
	ds_read_b32 v109, v4 offset:660
	ds_read_b32 v110, v4 offset:792
	ds_read_b32 v111, v4 offset:924
	ds_read_b32 v112, v4 offset:32
	ds_read_b32 v113, v4 offset:164
	ds_read_b32 v114, v4 offset:296
	ds_read_b32 v115, v4 offset:428
	ds_read_b32 v116, v4 offset:560
	ds_read_b32 v117, v4 offset:692
	ds_read_b32 v118, v4 offset:824
	ds_read_b32 v119, v4 offset:956
	s_waitcnt lgkmcnt(8)
	v_cvt_pk_bf16_f32 v136, v104, v105
	v_cvt_pk_bf16_f32 v137, v106, v107
	v_cvt_pk_bf16_f32 v138, v108, v109
	v_cvt_pk_bf16_f32 v139, v110, v111
	global_store_dwordx4 v6, v[136:139], s[32:33] nt
	s_add_u32 s32, s32, s49
	s_addc_u32 s33, s33, 0
	ds_read_b32 v120, v4 offset:64
	ds_read_b32 v121, v4 offset:196
	ds_read_b32 v122, v4 offset:328
	ds_read_b32 v123, v4 offset:460
	ds_read_b32 v124, v4 offset:592
	ds_read_b32 v125, v4 offset:724
	ds_read_b32 v126, v4 offset:856
	ds_read_b32 v127, v4 offset:988
	s_waitcnt lgkmcnt(8)
	v_cvt_pk_bf16_f32 v140, v112, v113
	v_cvt_pk_bf16_f32 v141, v114, v115
	v_cvt_pk_bf16_f32 v142, v116, v117
	v_cvt_pk_bf16_f32 v143, v118, v119
	global_store_dwordx4 v6, v[140:143], s[32:33] nt
	s_add_u32 s32, s32, s49
	s_addc_u32 s33, s33, 0
	ds_read_b32 v128, v4 offset:96
	ds_read_b32 v129, v4 offset:228
	ds_read_b32 v130, v4 offset:360
	ds_read_b32 v131, v4 offset:492
	ds_read_b32 v132, v4 offset:624
	ds_read_b32 v133, v4 offset:756
	ds_read_b32 v134, v4 offset:888
	ds_read_b32 v135, v4 offset:1020
	s_waitcnt lgkmcnt(8)
	v_cvt_pk_bf16_f32 v136, v120, v121
	v_cvt_pk_bf16_f32 v137, v122, v123
	v_cvt_pk_bf16_f32 v138, v124, v125
	v_cvt_pk_bf16_f32 v139, v126, v127
	global_store_dwordx4 v6, v[136:139], s[32:33] nt
	s_add_u32 s32, s32, s49
	s_addc_u32 s33, s33, 0
	s_waitcnt lgkmcnt(0)
	v_cvt_pk_bf16_f32 v140, v128, v129
	v_cvt_pk_bf16_f32 v141, v130, v131
	v_cvt_pk_bf16_f32 v142, v132, v133
	v_cvt_pk_bf16_f32 v143, v134, v135
	global_store_dwordx4 v6, v[140:143], s[32:33] nt
	s_add_u32 s32, s32, s49
	s_addc_u32 s33, s33, 0
	s_cmp_ge_u32 s20, 10240
	s_cbranch_scc1 .Ltt10_0_dr6
	s_cmp_lt_u32 s20, 2048
	s_cbranch_scc1 .Ltt10_0_r7_s0
	s_sub_u32 s25, s20, 2048
	s_and_b32 s41, s25, 7
	s_lshr_b32 s25, s25, 3
	s_lshr_b32 s27, s25, 6
	s_and_b32 s31, s25, 63
	s_lshl_b32 s27, s27, 3
	s_add_u32 s27, s27, s41
	s_mul_i32 s35, s27, 0x80000
	s_lshl_b32 s41, s31, 7
	s_add_u32 s35, s35, s41
	s_add_u32 s0, s66, s35
	s_addc_u32 s1, s67, 0
	s_mul_i32 s35, s31, 0x80000
	s_lshl_b32 s41, s27, 7
	s_add_u32 s35, s35, s41
	s_add_u32 s2, s68, s35
	s_addc_u32 s3, s69, 0
	s_mov_b32 s5, 0x2000
	s_mov_b32 s6, 0x10000
	s_mov_b32 s7, 0x4000
	s_branch .Ltt10_0_r7_e
